# gla_C: row rsqrt computed once per row via LDS instead of per element; dead DPP zero-inits removed; attention zero-init skipped when all lanes load
# speedup vs baseline: 1.0110x; 1.0037x over previous
; #define LAS __attribute__((address_space(3)))
; __device__ __forceinline__ float bf2f(unsigned short b) { return __uint_as_float(((unsigned)b) << 16); }
; __device__ __forceinline__ unsigned short f2bf(float f) { return (unsigned short)(cvt_pk_bf16(f, 0.f) & 0xffffu); }
; __device__ void gla_C(const Params& P, int l, int item, LAS unsigned char* lds) {
;     ...
;     __syncthreads();
; #pragma unroll
;     for (int rt = 0; rt < 16; ++rt)
; #pragma unroll
;         for (int jj = 0; jj < 4; ++jj) { const int t = rt * 16 + 4 * g + jj; float tot = 0.f;
; #pragma unroll
;             for (int ww = 0; ww < 8; ++ww) tot += SSQ[ww * 256 + t];
;             const float rs = rsqrtf(tot * (1.0f / 128.0f) + EPS);
;             const float gt = bf2f(*(const LAS unsigned short*)(GTL + t * 264 + (16 * w + c) * 2));
;             *(LAS unsigned short*)(OT + t * 272 + (16 * w + c) * 2) = f2bf(O[rt][jj] * rs * ng * (gt * __builtin_amdgcn_rcpf(1.0f + __expf(-gt)))); }
.LBB0_372:
	s_or_b64 exec, exec, s[0:1]
	v_lshl_add_u32 v66, v102, 2, 0
	s_waitcnt lgkmcnt(0)
	s_barrier
	v_and_b32_e32 v116, 0xff, v0
	v_lshlrev_b32_e32 v116, 2, v116
	ds_read2st64_b32 v[118:119], v116 offset1:4
	ds_read2st64_b32 v[120:121], v116 offset0:8 offset1:12
	ds_read2st64_b32 v[122:123], v116 offset0:16 offset1:20
	ds_read2st64_b32 v[124:125], v116 offset0:24 offset1:28
	v_add_u32_e32 v132, 0x23800, v66
	v_add_u32_e32 v116, 0x23800, v116
	s_waitcnt lgkmcnt(3)
	v_add_f32_e32 v117, 0, v118
	v_add_f32_e32 v117, v117, v119
	s_waitcnt lgkmcnt(2)
	v_add_f32_e32 v117, v117, v120
	v_add_f32_e32 v117, v117, v121
	s_waitcnt lgkmcnt(1)
	v_add_f32_e32 v117, v117, v122
	v_add_f32_e32 v117, v117, v123
	s_waitcnt lgkmcnt(0)
	v_add_f32_e32 v117, v117, v124
	v_add_f32_e32 v117, v117, v125
	v_fmamk_f32 v117, v117, 0x3c000000, v1
	v_cmp_gt_f32_e32 vcc, s33, v117
	v_mul_f32_e32 v118, 0x4b800000, v117
	s_nop 0
	v_cndmask_b32_e32 v117, v117, v118, vcc
	v_rsq_f32_e32 v117, v117
	s_nop 0
	v_mul_f32_e32 v118, 0x45800000, v117
	v_cndmask_b32_e32 v117, v117, v118, vcc
	ds_write_b32 v116, v117
	s_waitcnt lgkmcnt(0)
	s_barrier
	ds_read_b32 v243, v132 offset:0
	ds_read_b32 v242, v132 offset:4
	ds_read_b32 v241, v132 offset:8
	v_readlane_b32 s0, v255, 12
	v_lshlrev_b32_e32 v194, 4, v97
	v_add_u32_e32 v74, s0, v100
	s_movk_i32 s0, 0x420
	v_mad_u32_u24 v68, v157, s0, v74
	ds_read_u16 v240, v68
	s_waitcnt lgkmcnt(0)
	v_lshlrev_b32_e32 v68, 16, v240
	s_lshl_b32 s20, s31, 1
	v_mul_f32_e32 v69, 0xbfb8aa3b, v68
	v_exp_f32_e32 v69, v69
	ds_read_b32 v240, v132 offset:12
	s_add_i32 s45, s45, s94
	s_add_i32 s44, s44, s79
	v_add_f32_e32 v69, 1.0, v69
	v_rcp_f32_e32 v69, v69
	s_waitcnt lgkmcnt(1)
	v_mul_f32_e32 v62, v62, v243
	v_mul_f32_e32 v62, v99, v62
	v_mul_f32_e32 v67, v69, v68
	v_mul_f32_e32 v62, v67, v62
	v_add_u32_e32 v67, 4, v66
	v_cvt_pk_bf16_f32 v62, v62, v195
	v_mul_u32_u24_e32 v70, 0x440, v157
	v_add_u32_e32 v70, v95, v70
	ds_write_b16 v70, v62 offset:8192
	v_mad_u32_u24 v62, v96, s9, v74
	ds_read_u16 v243, v62
	ds_read_u16 v239, v62 offset:264
	ds_read_u16 v238, v62 offset:528
	ds_read_u16 v237, v62 offset:3960
	s_cmpk_gt_i32 s45, 0xff
	s_waitcnt lgkmcnt(3)
	v_lshlrev_b32_e32 v69, 16, v243
	v_mul_f32_e32 v70, 0xbfb8aa3b, v69
	v_exp_f32_e32 v70, v70
	ds_read_b32 v243, v132 offset:64
	v_add_f32_e32 v70, 1.0, v70
	v_rcp_f32_e32 v70, v70
	s_waitcnt lgkmcnt(4)
	v_mul_f32_e32 v63, v63, v242
	v_mul_f32_e32 v63, v99, v63
	v_mul_f32_e32 v68, v70, v69
	v_mul_f32_e32 v63, v68, v63
	v_cvt_pk_bf16_f32 v69, v63, v195
	v_add_u32_e32 v63, 8, v66
	v_mul_u32_u24_e32 v68, 0x110, v96
	v_add_u32_e32 v68, v95, v68
	ds_write_b16 v68, v69 offset:8192
	ds_read_u16 v242, v62 offset:4224
	s_waitcnt lgkmcnt(1)
	v_lshlrev_b32_e32 v70, 16, v239
	v_mul_f32_e32 v71, 0xbfb8aa3b, v70
	v_exp_f32_e32 v71, v71
	ds_read_b32 v239, v132 offset:68
	v_add_f32_e32 v71, 1.0, v71
	v_rcp_f32_e32 v71, v71
	s_waitcnt lgkmcnt(2)
	v_mul_f32_e32 v64, v64, v241
	v_mul_f32_e32 v64, v99, v64
	v_mul_f32_e32 v69, v71, v70
	v_mul_f32_e32 v64, v69, v64
	v_cvt_pk_bf16_f32 v69, v64, v195
	v_add_u32_e32 v64, 12, v66
	ds_write_b16 v68, v69 offset:8464
	ds_read_u16 v241, v62 offset:4488
	s_waitcnt lgkmcnt(1)
	v_lshlrev_b32_e32 v70, 16, v238
	v_mul_f32_e32 v71, 0xbfb8aa3b, v70
	v_exp_f32_e32 v71, v71
	ds_read_b32 v238, v132 offset:72
	v_add_f32_e32 v71, 1.0, v71
	v_rcp_f32_e32 v71, v71
	s_waitcnt lgkmcnt(2)
	v_mul_f32_e32 v65, v65, v240
	v_mul_f32_e32 v65, v99, v65
	v_mul_f32_e32 v69, v71, v70
	v_mul_f32_e32 v65, v69, v65
	v_cvt_pk_bf16_f32 v69, v65, v195
	v_add_u32_e32 v65, 64, v66
	ds_write_b16 v68, v69 offset:8736
	ds_read_u16 v240, v62 offset:4752
	s_waitcnt lgkmcnt(1)
	v_lshlrev_b32_e32 v70, 16, v237
	v_mul_f32_e32 v71, 0xbfb8aa3b, v70
	v_exp_f32_e32 v71, v71
	ds_read_b32 v237, v132 offset:76
	v_add_f32_e32 v71, 1.0, v71
	v_rcp_f32_e32 v71, v71
	s_waitcnt lgkmcnt(2)
	v_mul_f32_e32 v58, v58, v243
	v_mul_f32_e32 v58, v99, v58
	v_mul_f32_e32 v69, v71, v70
	v_mul_f32_e32 v58, v69, v58
	v_cvt_pk_bf16_f32 v69, v58, v195
	v_add_u32_e32 v58, 0x44, v66
	ds_write_b16 v68, v69 offset:12272
	ds_read_u16 v243, v62 offset:8184
	s_waitcnt lgkmcnt(1)
	v_lshlrev_b32_e32 v70, 16, v242
	v_mul_f32_e32 v71, 0xbfb8aa3b, v70
	v_exp_f32_e32 v71, v71
	ds_read_b32 v242, v132 offset:128
	v_add_f32_e32 v71, 1.0, v71
	v_rcp_f32_e32 v71, v71
	s_waitcnt lgkmcnt(2)
	v_mul_f32_e32 v59, v59, v239
	v_mul_f32_e32 v59, v99, v59
	v_mul_f32_e32 v69, v71, v70
	v_mul_f32_e32 v59, v69, v59
	v_cvt_pk_bf16_f32 v69, v59, v195
	v_add_u32_e32 v59, 0x48, v66
	ds_write_b16 v68, v69 offset:12544
	ds_read_u16 v239, v62 offset:8448
	s_waitcnt lgkmcnt(1)
	v_lshlrev_b32_e32 v69, 16, v241
	v_mul_f32_e32 v70, 0xbfb8aa3b, v69
	v_exp_f32_e32 v70, v70
	ds_read_b32 v241, v132 offset:132
	v_add_f32_e32 v70, 1.0, v70
	v_rcp_f32_e32 v70, v70
	s_waitcnt lgkmcnt(2)
	v_mul_f32_e32 v60, v60, v238
	v_mul_f32_e32 v60, v99, v60
	v_mul_f32_e32 v68, v70, v69
	v_mul_f32_e32 v60, v68, v60
	v_cvt_pk_bf16_f32 v70, v60, v195
	v_add_u32_e32 v60, 0x4c, v66
	ds_write_b16 v94, v70 offset:8192
	ds_read_u16 v238, v62 offset:8712
	s_waitcnt lgkmcnt(1)
	v_lshlrev_b32_e32 v69, 16, v240
	v_mul_f32_e32 v70, 0xbfb8aa3b, v69
	v_exp_f32_e32 v70, v70
	ds_read_b32 v240, v132 offset:136
	v_add_f32_e32 v70, 1.0, v70
	v_rcp_f32_e32 v70, v70
	s_waitcnt lgkmcnt(2)
	v_mul_f32_e32 v61, v61, v237
	v_mul_f32_e32 v61, v99, v61
	v_mul_f32_e32 v68, v70, v69
	v_mul_f32_e32 v61, v68, v61
	v_cvt_pk_bf16_f32 v70, v61, v195
	v_add_u32_e32 v61, 0x80, v66
	ds_write_b16 v94, v70 offset:8464
	ds_read_u16 v237, v62 offset:8976
	s_waitcnt lgkmcnt(1)
; #define LAS __attribute__((address_space(3)))
; __device__ __forceinline__ float bf2f(unsigned short b) { return __uint_as_float(((unsigned)b) << 16); }
; __device__ __forceinline__ unsigned short f2bf(float f) { return (unsigned short)(cvt_pk_bf16(f, 0.f) & 0xffffu); }
; __device__ void gla_C(const Params& P, int l, int item, LAS unsigned char* lds) {
;     ...
;     for (int rt = 0; rt < 16; ++rt)
; #pragma unroll
;         for (int jj = 0; jj < 4; ++jj) { const int t = rt * 16 + 4 * g + jj; float tot = 0.f;
; #pragma unroll
;             for (int ww = 0; ww < 8; ++ww) tot += SSQ[ww * 256 + t];
;             const float rs = rsqrtf(tot * (1.0f / 128.0f) + EPS);
;             const float gt = bf2f(*(const LAS unsigned short*)(GTL + t * 264 + (16 * w + c) * 2));
;             *(LAS unsigned short*)(OT + t * 272 + (16 * w + c) * 2) = f2bf(O[rt][jj] * rs * ng * (gt * __builtin_amdgcn_rcpf(1.0f + __expf(-gt)))); }
	v_lshlrev_b32_e32 v69, 16, v243
	v_mul_f32_e32 v70, 0xbfb8aa3b, v69
	v_exp_f32_e32 v70, v70
	ds_read_b32 v243, v132 offset:140
	v_add_f32_e32 v70, 1.0, v70
	v_rcp_f32_e32 v70, v70
	s_waitcnt lgkmcnt(2)
	v_mul_f32_e32 v54, v54, v242
	v_mul_f32_e32 v54, v99, v54
	v_mul_f32_e32 v68, v70, v69
	v_mul_f32_e32 v54, v68, v54
	v_add_u32_e32 v68, 0x84, v66
	v_cvt_pk_bf16_f32 v54, v54, v195
	ds_write_b16 v94, v54 offset:12000
	ds_read_u16 v242, v62 offset:12408
	s_waitcnt lgkmcnt(1)
	v_lshlrev_b32_e32 v69, 16, v239
	s_nop 0
	v_mul_f32_e32 v70, 0xbfb8aa3b, v69
	v_exp_f32_e32 v70, v70
	ds_read_b32 v239, v132 offset:192
	v_add_f32_e32 v70, 1.0, v70
	v_rcp_f32_e32 v70, v70
	s_waitcnt lgkmcnt(2)
	v_mul_f32_e32 v54, v55, v241
	v_mul_f32_e32 v54, v99, v54
	v_mul_f32_e32 v55, v70, v69
	v_mul_f32_e32 v54, v55, v54
	v_add_u32_e32 v69, 0x88, v66
	v_cvt_pk_bf16_f32 v70, v54, v195
	ds_write_b16 v94, v70 offset:12272
	ds_read_u16 v241, v62 offset:12672
	s_waitcnt lgkmcnt(1)
	v_lshlrev_b32_e32 v55, 16, v238
	v_mul_f32_e32 v70, 0xbfb8aa3b, v55
	v_exp_f32_e32 v70, v70
	ds_read_b32 v238, v132 offset:196
	v_add_f32_e32 v70, 1.0, v70
	v_rcp_f32_e32 v70, v70
	s_waitcnt lgkmcnt(2)
	v_mul_f32_e32 v54, v56, v240
	v_mul_f32_e32 v54, v99, v54
	v_mul_f32_e32 v55, v70, v55
	v_mul_f32_e32 v54, v55, v54
	v_add_u32_e32 v56, 0x8c, v66
	v_cvt_pk_bf16_f32 v70, v54, v195
	ds_write_b16 v94, v70 offset:12544
	ds_read_u16 v240, v62 offset:12936
	s_waitcnt lgkmcnt(1)
	v_lshlrev_b32_e32 v55, 16, v237
	v_mul_f32_e32 v70, 0xbfb8aa3b, v55
	v_exp_f32_e32 v70, v70
	ds_read_b32 v237, v132 offset:200
	v_add_f32_e32 v70, 1.0, v70
	v_rcp_f32_e32 v70, v70
	s_waitcnt lgkmcnt(2)
	v_mul_f32_e32 v54, v57, v243
	v_mul_f32_e32 v54, v99, v54
	v_mul_f32_e32 v55, v70, v55
	v_mul_f32_e32 v54, v55, v54
	v_add_u32_e32 v55, 0xc0, v66
	v_cvt_pk_bf16_f32 v54, v54, v195
	ds_write_b16 v93, v54 offset:8192
	ds_read_u16 v243, v62 offset:13200
	s_waitcnt lgkmcnt(1)
	v_lshlrev_b32_e32 v57, 16, v242
	s_nop 0
	v_mul_f32_e32 v70, 0xbfb8aa3b, v57
	v_exp_f32_e32 v70, v70
	ds_read_b32 v242, v132 offset:204
	v_add_f32_e32 v70, 1.0, v70
	v_rcp_f32_e32 v70, v70
	s_waitcnt lgkmcnt(2)
	v_mul_f32_e32 v50, v50, v239
	v_mul_f32_e32 v50, v99, v50
	v_mul_f32_e32 v54, v70, v57
	v_mul_f32_e32 v50, v54, v50
	v_add_u32_e32 v54, 0xc4, v66
	v_cvt_pk_bf16_f32 v50, v50, v195
	ds_write_b16 v93, v50 offset:11728
	ds_read_u16 v239, v62 offset:16632
	s_waitcnt lgkmcnt(1)
	v_lshlrev_b32_e32 v57, 16, v241
	s_nop 0
	v_mul_f32_e32 v70, 0xbfb8aa3b, v57
	v_exp_f32_e32 v70, v70
	ds_read_b32 v241, v132 offset:256
	v_add_f32_e32 v70, 1.0, v70
	v_rcp_f32_e32 v70, v70
	s_waitcnt lgkmcnt(2)
	v_mul_f32_e32 v50, v51, v238
	v_mul_f32_e32 v50, v99, v50
	v_mul_f32_e32 v51, v70, v57
	v_mul_f32_e32 v50, v51, v50
	v_add_u32_e32 v51, 0xc8, v66
	v_cvt_pk_bf16_f32 v50, v50, v195
	ds_write_b16 v93, v50 offset:12000
	ds_read_u16 v238, v62 offset:16896
	s_waitcnt lgkmcnt(1)
	v_lshlrev_b32_e32 v57, 16, v240
	s_nop 0
	v_mul_f32_e32 v70, 0xbfb8aa3b, v57
	v_exp_f32_e32 v70, v70
	ds_read_b32 v240, v132 offset:260
	v_add_f32_e32 v70, 1.0, v70
	v_rcp_f32_e32 v70, v70
	s_waitcnt lgkmcnt(2)
	v_mul_f32_e32 v50, v52, v237
	v_mul_f32_e32 v50, v99, v50
	v_mul_f32_e32 v52, v70, v57
	v_mul_f32_e32 v50, v52, v50
	v_cvt_pk_bf16_f32 v52, v50, v195
	v_add_u32_e32 v50, 0xcc, v66
	ds_write_b16 v93, v52 offset:12272
	ds_read_u16 v237, v62 offset:17160
	s_waitcnt lgkmcnt(1)
	v_lshlrev_b32_e32 v57, 16, v243
	s_nop 0
	v_mul_f32_e32 v70, 0xbfb8aa3b, v57
	v_exp_f32_e32 v70, v70
	ds_read_b32 v243, v132 offset:264
	v_add_f32_e32 v70, 1.0, v70
	v_rcp_f32_e32 v70, v70
	s_waitcnt lgkmcnt(2)
	v_mul_f32_e32 v52, v53, v242
	v_mul_f32_e32 v52, v99, v52
	v_mul_f32_e32 v53, v70, v57
	v_mul_f32_e32 v52, v53, v52
	v_cvt_pk_bf16_f32 v57, v52, v195
	ds_write_b16 v93, v57 offset:12544
	ds_read_u16 v242, v62 offset:17424
	s_waitcnt lgkmcnt(1)
	v_lshlrev_b32_e32 v53, 16, v239
	v_mul_f32_e32 v57, 0xbfb8aa3b, v53
	v_exp_f32_e32 v57, v57
	ds_read_b32 v239, v132 offset:268
	v_add_f32_e32 v57, 1.0, v57
	v_rcp_f32_e32 v57, v57
	s_waitcnt lgkmcnt(2)
	v_mul_f32_e32 v46, v46, v241
	v_mul_f32_e32 v46, v99, v46
	v_mul_f32_e32 v52, v57, v53
	v_mul_f32_e32 v46, v52, v46
	v_cvt_pk_bf16_f32 v46, v46, v195
	ds_write_b16 v92, v46 offset:8192
	ds_read_u16 v241, v62 offset:20856
	s_waitcnt lgkmcnt(1)
	v_lshlrev_b32_e32 v52, 16, v238
	v_mul_f32_e32 v53, 0xbfb8aa3b, v52
	v_exp_f32_e32 v53, v53
	ds_read_b32 v238, v132 offset:320
	v_add_f32_e32 v53, 1.0, v53
	v_rcp_f32_e32 v53, v53
	s_waitcnt lgkmcnt(2)
	v_mul_f32_e32 v46, v47, v240
	v_mul_f32_e32 v46, v99, v46
	v_mul_f32_e32 v47, v53, v52
	v_mul_f32_e32 v46, v47, v46
	v_cvt_pk_bf16_f32 v52, v46, v195
	ds_write_b16 v92, v52 offset:8464
	ds_read_u16 v240, v62 offset:21120
	s_waitcnt lgkmcnt(1)
	v_lshlrev_b32_e32 v47, 16, v237
	v_mul_f32_e32 v52, 0xbfb8aa3b, v47
	v_exp_f32_e32 v52, v52
	ds_read_b32 v237, v132 offset:324
	v_add_f32_e32 v52, 1.0, v52
	v_rcp_f32_e32 v52, v52
	s_waitcnt lgkmcnt(2)
	v_mul_f32_e32 v46, v48, v243
	v_mul_f32_e32 v46, v99, v46
	v_mul_f32_e32 v47, v52, v47
	v_mul_f32_e32 v46, v47, v46
	v_cvt_pk_bf16_f32 v48, v46, v195
	ds_write_b16 v92, v48 offset:8736
	ds_read_u16 v243, v62 offset:21384
	s_waitcnt lgkmcnt(1)
	v_lshlrev_b32_e32 v47, 16, v242
	v_mul_f32_e32 v48, 0xbfb8aa3b, v47
	v_exp_f32_e32 v48, v48
	ds_read_b32 v242, v132 offset:328
	v_add_f32_e32 v48, 1.0, v48
	v_rcp_f32_e32 v48, v48
	s_waitcnt lgkmcnt(2)
	v_mul_f32_e32 v46, v49, v239
	v_mul_f32_e32 v46, v99, v46
	v_mul_f32_e32 v47, v48, v47
	v_mul_f32_e32 v46, v47, v46
	v_cvt_pk_bf16_f32 v48, v46, v195
	ds_write_b16 v92, v48 offset:9008
	ds_read_u16 v239, v62 offset:21648
	s_waitcnt lgkmcnt(1)
; #define LAS __attribute__((address_space(3)))
; __device__ __forceinline__ float bf2f(unsigned short b) { return __uint_as_float(((unsigned)b) << 16); }
; __device__ __forceinline__ unsigned short f2bf(float f) { return (unsigned short)(cvt_pk_bf16(f, 0.f) & 0xffffu); }
; __device__ void gla_C(const Params& P, int l, int item, LAS unsigned char* lds) {
;     ...
;     for (int rt = 0; rt < 16; ++rt)
; #pragma unroll
;         for (int jj = 0; jj < 4; ++jj) { const int t = rt * 16 + 4 * g + jj; float tot = 0.f;
; #pragma unroll
;             for (int ww = 0; ww < 8; ++ww) tot += SSQ[ww * 256 + t];
;             const float rs = rsqrtf(tot * (1.0f / 128.0f) + EPS);
;             const float gt = bf2f(*(const LAS unsigned short*)(GTL + t * 264 + (16 * w + c) * 2));
;             *(LAS unsigned short*)(OT + t * 272 + (16 * w + c) * 2) = f2bf(O[rt][jj] * rs * ng * (gt * __builtin_amdgcn_rcpf(1.0f + __expf(-gt)))); }
	v_lshlrev_b32_e32 v47, 16, v241
	v_mul_f32_e32 v48, 0xbfb8aa3b, v47
	v_exp_f32_e32 v48, v48
	ds_read_b32 v241, v132 offset:332
	v_add_f32_e32 v48, 1.0, v48
	v_rcp_f32_e32 v48, v48
	s_waitcnt lgkmcnt(2)
	v_mul_f32_e32 v42, v42, v238
	v_mul_f32_e32 v42, v99, v42
	v_mul_f32_e32 v46, v48, v47
	v_mul_f32_e32 v42, v46, v42
	v_cvt_pk_bf16_f32 v42, v42, v195
	ds_write_b16 v92, v42 offset:12544
	ds_read_u16 v238, v62 offset:25080
	s_waitcnt lgkmcnt(1)
	v_lshlrev_b32_e32 v46, 16, v240
	v_mul_f32_e32 v47, 0xbfb8aa3b, v46
	v_exp_f32_e32 v47, v47
	ds_read_b32 v240, v132 offset:384
	v_add_f32_e32 v47, 1.0, v47
	v_rcp_f32_e32 v47, v47
	s_waitcnt lgkmcnt(2)
	v_mul_f32_e32 v42, v43, v237
	v_mul_f32_e32 v42, v99, v42
	v_mul_f32_e32 v43, v47, v46
	v_mul_f32_e32 v42, v43, v42
	v_cvt_pk_bf16_f32 v46, v42, v195
	ds_write_b16 v91, v46 offset:8192
	ds_read_u16 v237, v62 offset:25344
	s_waitcnt lgkmcnt(1)
	v_lshlrev_b32_e32 v43, 16, v243
	v_mul_f32_e32 v46, 0xbfb8aa3b, v43
	v_exp_f32_e32 v46, v46
	ds_read_b32 v243, v132 offset:388
	v_add_f32_e32 v46, 1.0, v46
	v_rcp_f32_e32 v46, v46
	s_waitcnt lgkmcnt(2)
	v_mul_f32_e32 v42, v44, v242
	v_mul_f32_e32 v42, v99, v42
	v_mul_f32_e32 v43, v46, v43
	v_mul_f32_e32 v42, v43, v42
	v_cvt_pk_bf16_f32 v44, v42, v195
	ds_write_b16 v91, v44 offset:8464
	ds_read_u16 v242, v62 offset:25608
	s_waitcnt lgkmcnt(1)
	v_lshlrev_b32_e32 v43, 16, v239
	v_mul_f32_e32 v44, 0xbfb8aa3b, v43
	v_exp_f32_e32 v44, v44
	ds_read_b32 v239, v132 offset:392
	v_add_f32_e32 v44, 1.0, v44
	v_rcp_f32_e32 v44, v44
	s_waitcnt lgkmcnt(2)
	v_mul_f32_e32 v42, v45, v241
	v_mul_f32_e32 v42, v99, v42
	v_mul_f32_e32 v43, v44, v43
	v_mul_f32_e32 v42, v43, v42
	v_cvt_pk_bf16_f32 v44, v42, v195
	ds_write_b16 v91, v44 offset:8736
	ds_read_u16 v241, v62 offset:25872
	s_waitcnt lgkmcnt(1)
	v_lshlrev_b32_e32 v43, 16, v238
	v_mul_f32_e32 v44, 0xbfb8aa3b, v43
	v_exp_f32_e32 v44, v44
	ds_read_b32 v238, v132 offset:396
	v_add_f32_e32 v44, 1.0, v44
	v_rcp_f32_e32 v44, v44
	s_waitcnt lgkmcnt(2)
	v_mul_f32_e32 v38, v38, v240
	v_mul_f32_e32 v38, v99, v38
	v_mul_f32_e32 v42, v44, v43
	v_mul_f32_e32 v38, v42, v38
	v_cvt_pk_bf16_f32 v38, v38, v195
	ds_write_b16 v91, v38 offset:12272
	ds_read_u16 v240, v62 offset:29304
	s_waitcnt lgkmcnt(1)
	v_lshlrev_b32_e32 v42, 16, v237
	v_mul_f32_e32 v43, 0xbfb8aa3b, v42
	v_exp_f32_e32 v43, v43
	ds_read_b32 v237, v132 offset:448
	v_add_f32_e32 v43, 1.0, v43
	v_rcp_f32_e32 v43, v43
	s_waitcnt lgkmcnt(2)
	v_mul_f32_e32 v38, v39, v243
	v_mul_f32_e32 v38, v99, v38
	v_mul_f32_e32 v39, v43, v42
	v_mul_f32_e32 v38, v39, v38
	v_cvt_pk_bf16_f32 v42, v38, v195
	ds_write_b16 v91, v42 offset:12544
	ds_read_u16 v243, v62 offset:29568
	s_waitcnt lgkmcnt(1)
	v_lshlrev_b32_e32 v39, 16, v242
	v_mul_f32_e32 v42, 0xbfb8aa3b, v39
	v_exp_f32_e32 v42, v42
	ds_read_b32 v242, v132 offset:452
	v_add_f32_e32 v42, 1.0, v42
	v_rcp_f32_e32 v42, v42
	s_waitcnt lgkmcnt(2)
	v_mul_f32_e32 v38, v40, v239
	v_mul_f32_e32 v38, v99, v38
	v_mul_f32_e32 v39, v42, v39
	v_mul_f32_e32 v38, v39, v38
	v_cvt_pk_bf16_f32 v40, v38, v195
	ds_write_b16 v90, v40 offset:8192
	ds_read_u16 v239, v62 offset:29832
	s_waitcnt lgkmcnt(1)
	v_lshlrev_b32_e32 v39, 16, v241
	v_mul_f32_e32 v40, 0xbfb8aa3b, v39
	v_exp_f32_e32 v40, v40
	ds_read_b32 v241, v132 offset:456
	v_add_f32_e32 v40, 1.0, v40
	v_rcp_f32_e32 v40, v40
	s_waitcnt lgkmcnt(2)
	v_mul_f32_e32 v38, v41, v238
	v_mul_f32_e32 v38, v99, v38
	v_mul_f32_e32 v39, v40, v39
	v_mul_f32_e32 v38, v39, v38
	v_cvt_pk_bf16_f32 v40, v38, v195
	ds_write_b16 v90, v40 offset:8464
	ds_read_u16 v238, v62 offset:30096
	s_waitcnt lgkmcnt(1)
	v_lshlrev_b32_e32 v39, 16, v240
	v_mul_f32_e32 v40, 0xbfb8aa3b, v39
	v_exp_f32_e32 v40, v40
	ds_read_b32 v240, v132 offset:460
	v_add_f32_e32 v40, 1.0, v40
	v_rcp_f32_e32 v40, v40
	s_waitcnt lgkmcnt(2)
	v_mul_f32_e32 v34, v34, v237
	v_mul_f32_e32 v34, v99, v34
	v_mul_f32_e32 v38, v40, v39
	v_mul_f32_e32 v34, v38, v34
	v_cvt_pk_bf16_f32 v34, v34, v195
	ds_write_b16 v90, v34 offset:12000
	ds_read_u16 v237, v62 offset:33528
	s_waitcnt lgkmcnt(1)
	v_lshlrev_b32_e32 v38, 16, v243
	v_mul_f32_e32 v39, 0xbfb8aa3b, v38
	v_exp_f32_e32 v39, v39
	ds_read_b32 v243, v132 offset:512
	v_add_f32_e32 v39, 1.0, v39
	v_rcp_f32_e32 v39, v39
	s_waitcnt lgkmcnt(2)
	v_mul_f32_e32 v34, v35, v242
	v_mul_f32_e32 v34, v99, v34
	v_mul_f32_e32 v35, v39, v38
	v_mul_f32_e32 v34, v35, v34
	v_cvt_pk_bf16_f32 v38, v34, v195
	ds_write_b16 v90, v38 offset:12272
	ds_read_u16 v242, v62 offset:33792
	s_waitcnt lgkmcnt(1)
	v_lshlrev_b32_e32 v35, 16, v239
	v_mul_f32_e32 v38, 0xbfb8aa3b, v35
	v_exp_f32_e32 v38, v38
	ds_read_b32 v239, v132 offset:516
	v_add_f32_e32 v38, 1.0, v38
	v_rcp_f32_e32 v38, v38
	s_waitcnt lgkmcnt(2)
	v_mul_f32_e32 v34, v36, v241
	v_mul_f32_e32 v34, v99, v34
	v_mul_f32_e32 v35, v38, v35
	v_mul_f32_e32 v34, v35, v34
	v_cvt_pk_bf16_f32 v36, v34, v195
	ds_write_b16 v90, v36 offset:12544
	ds_read_u16 v241, v62 offset:34056
	s_waitcnt lgkmcnt(1)
	v_lshlrev_b32_e32 v35, 16, v238
	v_mul_f32_e32 v36, 0xbfb8aa3b, v35
	v_exp_f32_e32 v36, v36
	ds_read_b32 v238, v132 offset:520
	v_add_f32_e32 v36, 1.0, v36
	v_rcp_f32_e32 v36, v36
	s_waitcnt lgkmcnt(2)
	v_mul_f32_e32 v34, v37, v240
	v_mul_f32_e32 v34, v99, v34
	v_mul_f32_e32 v35, v36, v35
	v_mul_f32_e32 v34, v35, v34
	v_cvt_pk_bf16_f32 v36, v34, v195
	ds_write_b16 v89, v36 offset:8192
	ds_read_u16 v240, v62 offset:34320
	s_waitcnt lgkmcnt(1)
	v_lshlrev_b32_e32 v35, 16, v237
	v_mul_f32_e32 v36, 0xbfb8aa3b, v35
	v_exp_f32_e32 v36, v36
	ds_read_b32 v237, v132 offset:524
	v_add_f32_e32 v36, 1.0, v36
	v_rcp_f32_e32 v36, v36
	s_waitcnt lgkmcnt(2)
; #define LAS __attribute__((address_space(3)))
; __device__ __forceinline__ float bf2f(unsigned short b) { return __uint_as_float(((unsigned)b) << 16); }
; __device__ __forceinline__ unsigned short f2bf(float f) { return (unsigned short)(cvt_pk_bf16(f, 0.f) & 0xffffu); }
; __device__ void gla_C(const Params& P, int l, int item, LAS unsigned char* lds) {
;     ...
;     for (int rt = 0; rt < 16; ++rt)
; #pragma unroll
;         for (int jj = 0; jj < 4; ++jj) { const int t = rt * 16 + 4 * g + jj; float tot = 0.f;
; #pragma unroll
;             for (int ww = 0; ww < 8; ++ww) tot += SSQ[ww * 256 + t];
;             const float rs = rsqrtf(tot * (1.0f / 128.0f) + EPS);
;             const float gt = bf2f(*(const LAS unsigned short*)(GTL + t * 264 + (16 * w + c) * 2));
;             *(LAS unsigned short*)(OT + t * 272 + (16 * w + c) * 2) = f2bf(O[rt][jj] * rs * ng * (gt * __builtin_amdgcn_rcpf(1.0f + __expf(-gt)))); }
	v_mul_f32_e32 v30, v30, v243
	v_mul_f32_e32 v30, v99, v30
	v_mul_f32_e32 v34, v36, v35
	v_mul_f32_e32 v30, v34, v30
	v_cvt_pk_bf16_f32 v30, v30, v195
	ds_write_b16 v89, v30 offset:11728
	ds_read_u16 v243, v62 offset:37752
	s_waitcnt lgkmcnt(1)
	v_lshlrev_b32_e32 v34, 16, v242
	v_mul_f32_e32 v35, 0xbfb8aa3b, v34
	v_exp_f32_e32 v35, v35
	ds_read_b32 v242, v132 offset:576
	v_add_f32_e32 v35, 1.0, v35
	v_rcp_f32_e32 v35, v35
	s_waitcnt lgkmcnt(2)
	v_mul_f32_e32 v30, v31, v239
	v_mul_f32_e32 v30, v99, v30
	v_mul_f32_e32 v31, v35, v34
	v_mul_f32_e32 v30, v31, v30
	v_cvt_pk_bf16_f32 v34, v30, v195
	ds_write_b16 v89, v34 offset:12000
	ds_read_u16 v239, v62 offset:38016
	s_waitcnt lgkmcnt(1)
	v_lshlrev_b32_e32 v31, 16, v241
	v_mul_f32_e32 v34, 0xbfb8aa3b, v31
	v_exp_f32_e32 v34, v34
	ds_read_b32 v241, v132 offset:580
	v_add_f32_e32 v34, 1.0, v34
	v_rcp_f32_e32 v34, v34
	s_waitcnt lgkmcnt(2)
	v_mul_f32_e32 v30, v32, v238
	v_mul_f32_e32 v30, v99, v30
	v_mul_f32_e32 v31, v34, v31
	v_mul_f32_e32 v30, v31, v30
	v_cvt_pk_bf16_f32 v32, v30, v195
	ds_write_b16 v89, v32 offset:12272
	ds_read_u16 v238, v62 offset:38280
	s_waitcnt lgkmcnt(1)
	v_lshlrev_b32_e32 v31, 16, v240
	v_mul_f32_e32 v32, 0xbfb8aa3b, v31
	v_exp_f32_e32 v32, v32
	ds_read_b32 v240, v132 offset:584
	v_add_f32_e32 v32, 1.0, v32
	v_rcp_f32_e32 v32, v32
	s_waitcnt lgkmcnt(2)
	v_mul_f32_e32 v30, v33, v237
	v_mul_f32_e32 v30, v99, v30
	v_mul_f32_e32 v31, v32, v31
	v_mul_f32_e32 v30, v31, v30
	v_cvt_pk_bf16_f32 v32, v30, v195
	ds_write_b16 v89, v32 offset:12544
	ds_read_u16 v237, v62 offset:38544
	s_waitcnt lgkmcnt(1)
	v_lshlrev_b32_e32 v31, 16, v243
	v_mul_f32_e32 v32, 0xbfb8aa3b, v31
	v_exp_f32_e32 v32, v32
	ds_read_b32 v243, v132 offset:588
	v_add_f32_e32 v32, 1.0, v32
	v_rcp_f32_e32 v32, v32
	s_waitcnt lgkmcnt(2)
	v_mul_f32_e32 v26, v26, v242
	v_mul_f32_e32 v26, v99, v26
	v_mul_f32_e32 v30, v32, v31
	v_mul_f32_e32 v26, v30, v26
	v_cvt_pk_bf16_f32 v26, v26, v195
	ds_write_b16 v88, v26 offset:8192
	ds_read_u16 v242, v62 offset:41976
	s_waitcnt lgkmcnt(1)
	v_lshlrev_b32_e32 v30, 16, v239
	v_mul_f32_e32 v31, 0xbfb8aa3b, v30
	v_exp_f32_e32 v31, v31
	ds_read_b32 v239, v132 offset:640
	v_add_f32_e32 v31, 1.0, v31
	v_rcp_f32_e32 v31, v31
	s_waitcnt lgkmcnt(2)
	v_mul_f32_e32 v26, v27, v241
	v_mul_f32_e32 v26, v99, v26
	v_mul_f32_e32 v27, v31, v30
	v_mul_f32_e32 v26, v27, v26
	v_cvt_pk_bf16_f32 v30, v26, v195
	ds_write_b16 v88, v30 offset:8464
	ds_read_u16 v241, v62 offset:42240
	s_waitcnt lgkmcnt(1)
	v_lshlrev_b32_e32 v27, 16, v238
	v_mul_f32_e32 v30, 0xbfb8aa3b, v27
	v_exp_f32_e32 v30, v30
	ds_read_b32 v238, v132 offset:644
	v_add_f32_e32 v30, 1.0, v30
	v_rcp_f32_e32 v30, v30
	s_waitcnt lgkmcnt(2)
	v_mul_f32_e32 v26, v28, v240
	v_mul_f32_e32 v26, v99, v26
	v_mul_f32_e32 v27, v30, v27
	v_mul_f32_e32 v26, v27, v26
	v_cvt_pk_bf16_f32 v28, v26, v195
	ds_write_b16 v88, v28 offset:8736
	ds_read_u16 v240, v62 offset:42504
	s_waitcnt lgkmcnt(1)
	v_lshlrev_b32_e32 v27, 16, v237
	v_mul_f32_e32 v28, 0xbfb8aa3b, v27
	v_exp_f32_e32 v28, v28
	ds_read_b32 v237, v132 offset:648
	v_add_f32_e32 v28, 1.0, v28
	v_rcp_f32_e32 v28, v28
	s_waitcnt lgkmcnt(2)
	v_mul_f32_e32 v26, v29, v243
	v_mul_f32_e32 v26, v99, v26
	v_mul_f32_e32 v27, v28, v27
	v_mul_f32_e32 v26, v27, v26
	v_cvt_pk_bf16_f32 v28, v26, v195
	ds_write_b16 v88, v28 offset:9008
	ds_read_u16 v243, v62 offset:42768
	s_waitcnt lgkmcnt(1)
	v_lshlrev_b32_e32 v27, 16, v242
	v_mul_f32_e32 v28, 0xbfb8aa3b, v27
	v_exp_f32_e32 v28, v28
	ds_read_b32 v242, v132 offset:652
	v_add_f32_e32 v28, 1.0, v28
	v_rcp_f32_e32 v28, v28
	s_waitcnt lgkmcnt(2)
	v_mul_f32_e32 v22, v22, v239
	v_mul_f32_e32 v22, v99, v22
	v_mul_f32_e32 v26, v28, v27
	v_mul_f32_e32 v22, v26, v22
	v_cvt_pk_bf16_f32 v22, v22, v195
	ds_write_b16 v88, v22 offset:12544
	ds_read_u16 v239, v62 offset:46200
	s_waitcnt lgkmcnt(1)
	v_lshlrev_b32_e32 v26, 16, v241
	v_mul_f32_e32 v27, 0xbfb8aa3b, v26
	v_exp_f32_e32 v27, v27
	ds_read_b32 v241, v132 offset:704
	v_add_f32_e32 v27, 1.0, v27
	v_rcp_f32_e32 v27, v27
	s_waitcnt lgkmcnt(2)
	v_mul_f32_e32 v22, v23, v238
	v_mul_f32_e32 v22, v99, v22
	v_mul_f32_e32 v23, v27, v26
	v_mul_f32_e32 v22, v23, v22
	v_cvt_pk_bf16_f32 v26, v22, v195
	ds_write_b16 v87, v26 offset:8192
	ds_read_u16 v238, v62 offset:46464
	s_waitcnt lgkmcnt(1)
	v_lshlrev_b32_e32 v23, 16, v240
	v_mul_f32_e32 v26, 0xbfb8aa3b, v23
	v_exp_f32_e32 v26, v26
	ds_read_b32 v240, v132 offset:708
	v_add_f32_e32 v26, 1.0, v26
	v_rcp_f32_e32 v26, v26
	s_waitcnt lgkmcnt(2)
	v_mul_f32_e32 v22, v24, v237
	v_mul_f32_e32 v22, v99, v22
	v_mul_f32_e32 v23, v26, v23
	v_mul_f32_e32 v22, v23, v22
	v_cvt_pk_bf16_f32 v24, v22, v195
	ds_write_b16 v87, v24 offset:8464
	ds_read_u16 v237, v62 offset:46728
	s_waitcnt lgkmcnt(1)
	v_lshlrev_b32_e32 v23, 16, v243
	v_mul_f32_e32 v24, 0xbfb8aa3b, v23
	v_exp_f32_e32 v24, v24
	ds_read_b32 v243, v132 offset:712
	v_add_f32_e32 v24, 1.0, v24
	v_rcp_f32_e32 v24, v24
	s_waitcnt lgkmcnt(2)
	v_mul_f32_e32 v22, v25, v242
	v_mul_f32_e32 v22, v99, v22
	v_mul_f32_e32 v23, v24, v23
	v_mul_f32_e32 v22, v23, v22
	v_cvt_pk_bf16_f32 v24, v22, v195
	ds_write_b16 v87, v24 offset:8736
	ds_read_u16 v242, v62 offset:46992
	s_waitcnt lgkmcnt(1)
	v_lshlrev_b32_e32 v23, 16, v239
	v_mul_f32_e32 v24, 0xbfb8aa3b, v23
	v_exp_f32_e32 v24, v24
	ds_read_b32 v239, v132 offset:716
	v_add_f32_e32 v24, 1.0, v24
	v_rcp_f32_e32 v24, v24
	s_waitcnt lgkmcnt(2)
	v_mul_f32_e32 v18, v18, v241
	v_mul_f32_e32 v18, v99, v18
	v_mul_f32_e32 v22, v24, v23
	v_mul_f32_e32 v18, v22, v18
	v_cvt_pk_bf16_f32 v18, v18, v195
	ds_write_b16 v87, v18 offset:12272
	ds_read_u16 v241, v62 offset:50424
	s_waitcnt lgkmcnt(1)
; #define LAS __attribute__((address_space(3)))
; __device__ __forceinline__ float bf2f(unsigned short b) { return __uint_as_float(((unsigned)b) << 16); }
; __device__ __forceinline__ unsigned short f2bf(float f) { return (unsigned short)(cvt_pk_bf16(f, 0.f) & 0xffffu); }
; __device__ void gla_C(const Params& P, int l, int item, LAS unsigned char* lds) {
;     ...
;     for (int rt = 0; rt < 16; ++rt)
; #pragma unroll
;         for (int jj = 0; jj < 4; ++jj) { const int t = rt * 16 + 4 * g + jj; float tot = 0.f;
; #pragma unroll
;             for (int ww = 0; ww < 8; ++ww) tot += SSQ[ww * 256 + t];
;             const float rs = rsqrtf(tot * (1.0f / 128.0f) + EPS);
;             const float gt = bf2f(*(const LAS unsigned short*)(GTL + t * 264 + (16 * w + c) * 2));
;             *(LAS unsigned short*)(OT + t * 272 + (16 * w + c) * 2) = f2bf(O[rt][jj] * rs * ng * (gt * __builtin_amdgcn_rcpf(1.0f + __expf(-gt)))); }
	v_lshlrev_b32_e32 v22, 16, v238
	v_mul_f32_e32 v23, 0xbfb8aa3b, v22
	v_exp_f32_e32 v23, v23
	ds_read_b32 v238, v132 offset:768
	v_add_f32_e32 v23, 1.0, v23
	v_rcp_f32_e32 v23, v23
	s_waitcnt lgkmcnt(2)
	v_mul_f32_e32 v18, v19, v240
	v_mul_f32_e32 v18, v99, v18
	v_mul_f32_e32 v19, v23, v22
	v_mul_f32_e32 v18, v19, v18
	v_cvt_pk_bf16_f32 v22, v18, v195
	ds_write_b16 v87, v22 offset:12544
	ds_read_u16 v240, v62 offset:50688
	v_add_u32_e32 v26, 0, v194
	s_waitcnt lgkmcnt(1)
	v_lshlrev_b32_e32 v19, 16, v237
	v_mul_f32_e32 v22, 0xbfb8aa3b, v19
	v_exp_f32_e32 v22, v22
	ds_read_b32 v237, v132 offset:772
	v_add_f32_e32 v22, 1.0, v22
	v_rcp_f32_e32 v22, v22
	s_waitcnt lgkmcnt(2)
	v_mul_f32_e32 v18, v20, v243
	v_mul_f32_e32 v18, v99, v18
	v_mul_f32_e32 v19, v22, v19
	v_mul_f32_e32 v18, v19, v18
	v_cvt_pk_bf16_f32 v20, v18, v195
	ds_write_b16 v86, v20 offset:8192
	ds_read_u16 v243, v62 offset:50952
	s_waitcnt lgkmcnt(1)
	v_lshlrev_b32_e32 v19, 16, v242
	v_mul_f32_e32 v20, 0xbfb8aa3b, v19
	v_exp_f32_e32 v20, v20
	ds_read_b32 v242, v132 offset:776
	v_add_f32_e32 v20, 1.0, v20
	v_rcp_f32_e32 v20, v20
	s_waitcnt lgkmcnt(2)
	v_mul_f32_e32 v18, v21, v239
	v_mul_f32_e32 v18, v99, v18
	v_mul_f32_e32 v19, v20, v19
	v_mul_f32_e32 v18, v19, v18
	v_cvt_pk_bf16_f32 v20, v18, v195
	ds_write_b16 v86, v20 offset:8464
	ds_read_u16 v239, v62 offset:51216
	s_waitcnt lgkmcnt(1)
	v_lshlrev_b32_e32 v19, 16, v241
	v_mul_f32_e32 v20, 0xbfb8aa3b, v19
	v_exp_f32_e32 v20, v20
	ds_read_b32 v241, v132 offset:780
	v_add_f32_e32 v20, 1.0, v20
	v_rcp_f32_e32 v20, v20
	s_waitcnt lgkmcnt(2)
	v_mul_f32_e32 v14, v14, v238
	v_mul_f32_e32 v14, v99, v14
	v_mul_f32_e32 v18, v20, v19
	v_mul_f32_e32 v14, v18, v14
	v_cvt_pk_bf16_f32 v14, v14, v195
	ds_write_b16 v86, v14 offset:12000
	ds_read_u16 v238, v62 offset:54648
	s_waitcnt lgkmcnt(1)
	v_lshlrev_b32_e32 v18, 16, v240
	v_mul_f32_e32 v19, 0xbfb8aa3b, v18
	v_exp_f32_e32 v19, v19
	ds_read_b32 v240, v132 offset:832
	v_add_f32_e32 v19, 1.0, v19
	v_rcp_f32_e32 v19, v19
	s_waitcnt lgkmcnt(2)
	v_mul_f32_e32 v14, v15, v237
	v_mul_f32_e32 v14, v99, v14
	v_mul_f32_e32 v15, v19, v18
	v_mul_f32_e32 v14, v15, v14
	v_cvt_pk_bf16_f32 v18, v14, v195
	ds_write_b16 v86, v18 offset:12272
	ds_read_u16 v237, v62 offset:54912
	s_waitcnt lgkmcnt(1)
	v_lshlrev_b32_e32 v15, 16, v243
	v_mul_f32_e32 v18, 0xbfb8aa3b, v15
	v_exp_f32_e32 v18, v18
	ds_read_b32 v243, v132 offset:836
	v_add_f32_e32 v18, 1.0, v18
	v_rcp_f32_e32 v18, v18
	s_waitcnt lgkmcnt(2)
	v_mul_f32_e32 v14, v16, v242
	v_mul_f32_e32 v14, v99, v14
	v_mul_f32_e32 v15, v18, v15
	v_mul_f32_e32 v14, v15, v14
	v_cvt_pk_bf16_f32 v16, v14, v195
	ds_write_b16 v86, v16 offset:12544
	ds_read_u16 v242, v62 offset:55176
	s_waitcnt lgkmcnt(1)
	v_lshlrev_b32_e32 v15, 16, v239
	v_mul_f32_e32 v16, 0xbfb8aa3b, v15
	v_exp_f32_e32 v16, v16
	ds_read_b32 v239, v132 offset:840
	v_add_f32_e32 v16, 1.0, v16
	v_rcp_f32_e32 v16, v16
	s_waitcnt lgkmcnt(2)
	v_mul_f32_e32 v14, v17, v241
	v_mul_f32_e32 v14, v99, v14
	v_mul_f32_e32 v15, v16, v15
	v_mul_f32_e32 v14, v15, v14
	v_cvt_pk_bf16_f32 v16, v14, v195
	ds_write_b16 v85, v16 offset:8192
	ds_read_u16 v241, v62 offset:55440
	s_waitcnt lgkmcnt(1)
	v_lshlrev_b32_e32 v15, 16, v238
	v_mul_f32_e32 v16, 0xbfb8aa3b, v15
	v_exp_f32_e32 v16, v16
	ds_read_b32 v238, v132 offset:844
	v_add_f32_e32 v16, 1.0, v16
	v_rcp_f32_e32 v16, v16
	s_waitcnt lgkmcnt(2)
	v_mul_f32_e32 v10, v10, v240
	v_mul_f32_e32 v10, v99, v10
	v_mul_f32_e32 v14, v16, v15
	v_mul_f32_e32 v10, v14, v10
	v_cvt_pk_bf16_f32 v10, v10, v195
	ds_write_b16 v85, v10 offset:11728
	ds_read_u16 v240, v62 offset:58872
	s_waitcnt lgkmcnt(1)
	v_lshlrev_b32_e32 v14, 16, v237
	v_mul_f32_e32 v15, 0xbfb8aa3b, v14
	v_exp_f32_e32 v15, v15
	ds_read_b32 v237, v132 offset:896
	v_add_f32_e32 v15, 1.0, v15
	v_rcp_f32_e32 v15, v15
	s_waitcnt lgkmcnt(2)
	v_mul_f32_e32 v10, v11, v243
	v_mul_f32_e32 v10, v99, v10
	v_mul_f32_e32 v11, v15, v14
	v_mul_f32_e32 v10, v11, v10
	v_cvt_pk_bf16_f32 v14, v10, v195
	ds_write_b16 v85, v14 offset:12000
	ds_read_u16 v243, v62 offset:59136
	s_waitcnt lgkmcnt(1)
	v_lshlrev_b32_e32 v11, 16, v242
	v_mul_f32_e32 v14, 0xbfb8aa3b, v11
	v_exp_f32_e32 v14, v14
	ds_read_b32 v242, v132 offset:900
	v_add_f32_e32 v14, 1.0, v14
	v_rcp_f32_e32 v14, v14
	s_waitcnt lgkmcnt(2)
	v_mul_f32_e32 v10, v12, v239
	v_mul_f32_e32 v10, v99, v10
	v_mul_f32_e32 v11, v14, v11
	v_mul_f32_e32 v10, v11, v10
	v_cvt_pk_bf16_f32 v12, v10, v195
	ds_write_b16 v85, v12 offset:12272
	ds_read_u16 v239, v62 offset:59400
	s_waitcnt lgkmcnt(1)
	v_lshlrev_b32_e32 v11, 16, v241
	v_mul_f32_e32 v12, 0xbfb8aa3b, v11
	v_exp_f32_e32 v12, v12
	ds_read_b32 v241, v132 offset:904
	v_add_f32_e32 v12, 1.0, v12
	v_rcp_f32_e32 v12, v12
	s_waitcnt lgkmcnt(2)
	v_mul_f32_e32 v10, v13, v238
	v_mul_f32_e32 v10, v99, v10
	v_mul_f32_e32 v11, v12, v11
	v_mul_f32_e32 v10, v11, v10
	v_cvt_pk_bf16_f32 v12, v10, v195
	ds_write_b16 v85, v12 offset:12544
	ds_read_u16 v238, v62 offset:59664
	s_waitcnt lgkmcnt(1)
	v_lshlrev_b32_e32 v11, 16, v240
	v_mul_f32_e32 v12, 0xbfb8aa3b, v11
	v_exp_f32_e32 v12, v12
	ds_read_b32 v240, v132 offset:908
	v_add_f32_e32 v12, 1.0, v12
	v_rcp_f32_e32 v12, v12
	s_waitcnt lgkmcnt(2)
	v_mul_f32_e32 v6, v6, v237
	v_mul_f32_e32 v6, v99, v6
	v_mul_f32_e32 v10, v12, v11
	v_mul_f32_e32 v6, v10, v6
	v_cvt_pk_bf16_f32 v6, v6, v195
	ds_write_b16 v84, v6 offset:8192
	ds_read_u16 v237, v62 offset:63096
	s_waitcnt lgkmcnt(1)
; #define LAS __attribute__((address_space(3)))
; __device__ __forceinline__ float bf2f(unsigned short b) { return __uint_as_float(((unsigned)b) << 16); }
; __device__ __forceinline__ unsigned short f2bf(float f) { return (unsigned short)(cvt_pk_bf16(f, 0.f) & 0xffffu); }
; __device__ void gla_C(const Params& P, int l, int item, LAS unsigned char* lds) {
;     ...
; #pragma unroll
;     for (int rt = 0; rt < 16; ++rt)
; #pragma unroll
;         for (int jj = 0; jj < 4; ++jj) { const int t = rt * 16 + 4 * g + jj; float tot = 0.f;
; #pragma unroll
;             for (int ww = 0; ww < 8; ++ww) tot += SSQ[ww * 256 + t];
;             const float rs = rsqrtf(tot * (1.0f / 128.0f) + EPS);
;             const float gt = bf2f(*(const LAS unsigned short*)(GTL + t * 264 + (16 * w + c) * 2));
;             *(LAS unsigned short*)(OT + t * 272 + (16 * w + c) * 2) = f2bf(O[rt][jj] * rs * ng * (gt * __builtin_amdgcn_rcpf(1.0f + __expf(-gt)))); }
;     __syncthreads();
; #pragma unroll
;     for (int i = 0; i < 8; ++i) { const int p = tid + i * NTHR, r = p >> 4, sg = p & 15;
;         *(u32x4*)(Z + (size_t)(row0 + r) * ZC + ZG + h * 128 + sg * 8) = *(const LAS u32x4*)(OT + r * 272 + sg * 16); }
;     __syncthreads();
	v_lshlrev_b32_e32 v10, 16, v243
	v_mul_f32_e32 v11, 0xbfb8aa3b, v10
	v_exp_f32_e32 v11, v11
	ds_read_b32 v243, v132 offset:960
	v_add_f32_e32 v11, 1.0, v11
	v_rcp_f32_e32 v11, v11
	s_waitcnt lgkmcnt(2)
	v_mul_f32_e32 v6, v7, v242
	v_mul_f32_e32 v6, v99, v6
	v_mul_f32_e32 v7, v11, v10
	v_mul_f32_e32 v6, v7, v6
	v_cvt_pk_bf16_f32 v10, v6, v195
	ds_write_b16 v84, v10 offset:8464
	ds_read_u16 v242, v62 offset:63360
	s_waitcnt lgkmcnt(1)
	v_lshlrev_b32_e32 v7, 16, v239
	v_mul_f32_e32 v10, 0xbfb8aa3b, v7
	v_exp_f32_e32 v10, v10
	ds_read_b32 v239, v132 offset:964
	v_add_f32_e32 v10, 1.0, v10
	v_rcp_f32_e32 v10, v10
	s_waitcnt lgkmcnt(2)
	v_mul_f32_e32 v6, v8, v241
	v_mul_f32_e32 v6, v99, v6
	v_mul_f32_e32 v7, v10, v7
	v_mul_f32_e32 v6, v7, v6
	v_cvt_pk_bf16_f32 v8, v6, v195
	ds_write_b16 v84, v8 offset:8736
	ds_read_u16 v241, v62 offset:63624
	s_waitcnt lgkmcnt(1)
	v_lshlrev_b32_e32 v7, 16, v238
	v_mul_f32_e32 v8, 0xbfb8aa3b, v7
	v_exp_f32_e32 v8, v8
	ds_read_b32 v238, v132 offset:968
	v_add_f32_e32 v8, 1.0, v8
	v_rcp_f32_e32 v8, v8
	s_waitcnt lgkmcnt(2)
	v_mul_f32_e32 v6, v9, v240
	v_mul_f32_e32 v6, v99, v6
	v_mul_f32_e32 v7, v8, v7
	v_mul_f32_e32 v6, v7, v6
	v_cvt_pk_bf16_f32 v10, v6, v195
	ds_write_b16 v84, v10 offset:9008
	v_mad_i64_i32 v[6:7], s[0:1], v156, s25, 0
	ds_read_u16 v240, v62 offset:63888
	s_waitcnt lgkmcnt(1)
	v_lshlrev_b32_e32 v11, 16, v237
	ds_read_b32 v237, v132 offset:972
	v_mul_f32_e32 v8, 0xbfb8aa3b, v11
	v_exp_f32_e32 v12, v8
	v_mad_i64_i32 v[8:9], s[0:1], v155, s25, 0
	v_add_f32_e32 v12, 1.0, v12
	v_rcp_f32_e32 v12, v12
	s_waitcnt lgkmcnt(2)
	v_mul_f32_e32 v2, v2, v243
	v_mul_f32_e32 v2, v99, v2
	v_mul_f32_e32 v10, v12, v11
	v_mul_f32_e32 v2, v10, v2
	v_cvt_pk_bf16_f32 v2, v2, v195
	ds_write_b16 v84, v2 offset:12544
	v_lshl_add_u64 v[8:9], s[28:29], 0, v[8:9]
	s_nop 0
	s_waitcnt lgkmcnt(0)
	v_lshlrev_b32_e32 v14, 16, v242
	v_mul_f32_e32 v12, 0xbfb8aa3b, v14
	v_exp_f32_e32 v15, v12
	s_nop 0
	v_lshl_add_u64 v[8:9], v[8:9], 0, s[20:21]
	v_add_f32_e32 v15, 1.0, v15
	v_rcp_f32_e32 v15, v15
	s_waitcnt lgkmcnt(0)
	v_mul_f32_e32 v2, v3, v239
	v_mul_f32_e32 v2, v99, v2
	v_mul_f32_e32 v3, v15, v14
	v_mul_f32_e32 v2, v3, v2
	v_cvt_pk_bf16_f32 v16, v2, v195
	ds_write_b16 v84, v16 offset:12816
	v_lshl_add_u64 v[8:9], v[8:9], 0, v[194:195]
	s_nop 0
	v_mad_i64_i32 v[10:11], s[0:1], v154, s25, 0
	s_waitcnt lgkmcnt(0)
	v_lshlrev_b32_e32 v15, 16, v241
	v_mul_f32_e32 v16, 0xbfb8aa3b, v15
	v_exp_f32_e32 v16, v16
	s_nop 0
	v_mad_i64_i32 v[12:13], s[0:1], v153, s25, 0
	v_add_f32_e32 v16, 1.0, v16
	v_rcp_f32_e32 v16, v16
	s_waitcnt lgkmcnt(0)
	v_mul_f32_e32 v4, v4, v238
	v_mul_f32_e32 v4, v99, v4
	v_mul_f32_e32 v14, v16, v15
	v_mul_f32_e32 v4, v14, v4
	v_cvt_pk_bf16_f32 v4, v4, v195
	ds_write_b16 v84, v4 offset:13088
	v_mad_i64_i32 v[2:3], s[0:1], v152, s25, 0
	s_nop 0
	s_waitcnt lgkmcnt(0)
	v_lshlrev_b32_e32 v14, 16, v240
	v_lshl_add_u64 v[2:3], s[28:29], 0, v[2:3]
	v_mul_f32_e32 v15, 0xbfb8aa3b, v14
	v_exp_f32_e32 v15, v15
	s_nop 0
	v_lshl_add_u64 v[2:3], v[2:3], 0, s[20:21]
	v_mad_i64_i32 v[18:19], s[0:1], v151, s25, 0
	v_add_f32_e32 v15, 1.0, v15
	v_rcp_f32_e32 v15, v15
	s_waitcnt lgkmcnt(0)
	v_mul_f32_e32 v4, v5, v237
	v_mul_f32_e32 v4, v99, v4
	v_mul_f32_e32 v5, v15, v14
	v_mul_f32_e32 v4, v5, v4
	v_cvt_pk_bf16_f32 v4, v4, v195
	ds_write_b16 v84, v4 offset:13360
	v_add_u32_e32 v4, v26, v83
	s_waitcnt lgkmcnt(0)
	s_barrier
	ds_read_b128 v[14:17], v4 offset:8192
	v_lshl_add_u64 v[4:5], s[28:29], 0, v[6:7]
	v_lshl_add_u64 v[4:5], v[4:5], 0, s[20:21]
	v_lshl_add_u64 v[24:25], v[4:5], 0, v[194:195]
	v_add_u32_e32 v4, v26, v82
	ds_read_b128 v[4:7], v4 offset:8192
	s_waitcnt lgkmcnt(1)
	global_store_dwordx4 v[24:25], v[14:17], off offset:2048
	v_lshl_add_u64 v[2:3], v[2:3], 0, v[194:195]
	v_mad_i64_i32 v[20:21], s[0:1], v150, s25, 0
	s_waitcnt lgkmcnt(0)
	global_store_dwordx4 v[8:9], v[4:7], off offset:2048
	v_lshl_add_u64 v[8:9], s[28:29], 0, v[10:11]
	v_lshl_add_u64 v[8:9], v[8:9], 0, s[20:21]
	v_add_u32_e32 v4, v26, v81
	ds_read_b128 v[4:7], v4 offset:8192
	v_lshl_add_u64 v[14:15], v[8:9], 0, v[194:195]
	v_add_u32_e32 v8, v26, v80
	ds_read_b128 v[8:11], v8 offset:8192
	v_mad_i64_i32 v[22:23], s[0:1], v101, s25, 0
	s_waitcnt lgkmcnt(1)
	global_store_dwordx4 v[14:15], v[4:7], off offset:2048
	s_nop 1
	v_lshl_add_u64 v[4:5], s[28:29], 0, v[12:13]
	v_lshl_add_u64 v[4:5], v[4:5], 0, s[20:21]
	v_lshl_add_u64 v[4:5], v[4:5], 0, v[194:195]
	s_waitcnt lgkmcnt(0)
	global_store_dwordx4 v[4:5], v[8:11], off offset:2048
	v_add_u32_e32 v4, v26, v79
	ds_read_b128 v[4:7], v4 offset:8192
	v_add_u32_e32 v8, v26, v78
	ds_read_b128 v[8:11], v8 offset:8192
	s_waitcnt lgkmcnt(1)
	global_store_dwordx4 v[2:3], v[4:7], off offset:2048
	v_lshl_add_u64 v[2:3], s[28:29], 0, v[18:19]
	v_lshl_add_u64 v[2:3], v[2:3], 0, s[20:21]
	v_lshl_add_u64 v[2:3], v[2:3], 0, v[194:195]
	s_waitcnt lgkmcnt(0)
	global_store_dwordx4 v[2:3], v[8:11], off offset:2048
	v_add_u32_e32 v2, v26, v77
	ds_read_b128 v[2:5], v2 offset:8192
	v_lshl_add_u64 v[6:7], s[28:29], 0, v[20:21]
	v_lshl_add_u64 v[6:7], v[6:7], 0, s[20:21]
	v_lshl_add_u64 v[10:11], v[6:7], 0, v[194:195]
	v_add_u32_e32 v6, v26, v76
	ds_read_b128 v[6:9], v6 offset:8192
	s_waitcnt lgkmcnt(1)
	global_store_dwordx4 v[10:11], v[2:5], off offset:2048
	s_nop 1
	v_lshl_add_u64 v[2:3], s[28:29], 0, v[22:23]
	v_lshl_add_u64 v[2:3], v[2:3], 0, s[20:21]
	v_lshl_add_u64 v[2:3], v[2:3], 0, v[194:195]
	s_waitcnt lgkmcnt(0)
	global_store_dwordx4 v[2:3], v[6:9], off offset:2048
	s_barrier
	s_cbranch_scc1 .LBB0_446

; __device__ void gla_C(const Params& P, int l, int item, LAS unsigned char* lds) {
;     ...
;     {
; #pragma unroll
;         for (int rt = 0; rt < 16; ++rt) {
;             float sv[4];
; #pragma unroll
;             for (int jj = 0; jj < 4; ++jj) sv[jj] = O[rt][jj] * O[rt][jj];
; #pragma unroll
;             for (int jj = 0; jj < 4; ++jj) sv[jj] = dpp_row_sum16(sv[jj]);
;             if (c == 0) {
; #pragma unroll
;                 for (int jj = 0; jj < 4; ++jj) SSQ[w * 256 + rt * 16 + 4 * g + jj] = sv[jj]; }
;         }
;     }
.LBB0_412:
	v_pk_mul_f32 v[70:71], v[64:65], v[64:65]
	v_pk_mul_f32 v[66:67], v[62:63], v[62:63]
	s_nop 1
	v_mov_b32_dpp v68, v66 quad_perm:[1,0,3,2] row_mask:0xf bank_mask:0xf
	v_mov_b32_dpp v69, v67 quad_perm:[1,0,3,2] row_mask:0xf bank_mask:0xf
	v_mov_b32_dpp v72, v70 quad_perm:[1,0,3,2] row_mask:0xf bank_mask:0xf
	v_mov_b32_dpp v73, v71 quad_perm:[1,0,3,2] row_mask:0xf bank_mask:0xf
	v_pk_fma_f32 v[66:67], v[62:63], v[62:63], v[68:69]
	v_pk_fma_f32 v[70:71], v[64:65], v[64:65], v[72:73]
	s_nop 0
	v_mov_b32_dpp v68, v66 quad_perm:[2,3,0,1] row_mask:0xf bank_mask:0xf
	v_mov_b32_dpp v69, v67 quad_perm:[2,3,0,1] row_mask:0xf bank_mask:0xf
	v_mov_b32_dpp v72, v70 quad_perm:[2,3,0,1] row_mask:0xf bank_mask:0xf
	v_mov_b32_dpp v73, v71 quad_perm:[2,3,0,1] row_mask:0xf bank_mask:0xf
	v_pk_add_f32 v[66:67], v[66:67], v[68:69]
	v_pk_add_f32 v[70:71], v[70:71], v[72:73]
	s_lshl_b32 s0, s2, 10
	v_mov_b32_dpp v68, v66 row_half_mirror row_mask:0xf bank_mask:0xf
	v_mov_b32_dpp v69, v67 row_half_mirror row_mask:0xf bank_mask:0xf
	v_mov_b32_dpp v72, v70 row_half_mirror row_mask:0xf bank_mask:0xf
	v_mov_b32_dpp v73, v71 row_half_mirror row_mask:0xf bank_mask:0xf
	s_add_i32 s0, s0, 0
	v_lshlrev_b32_e32 v74, 4, v157
	v_pk_add_f32 v[66:67], v[66:67], v[68:69]
	v_pk_add_f32 v[70:71], v[70:71], v[72:73]
	v_cmp_eq_u32_e32 vcc, 0, v97
	v_mov_b32_dpp v68, v66 row_mirror row_mask:0xf bank_mask:0xf
	v_mov_b32_dpp v69, v67 row_mirror row_mask:0xf bank_mask:0xf
	v_mov_b32_dpp v72, v70 row_mirror row_mask:0xf bank_mask:0xf
	v_mov_b32_dpp v73, v71 row_mirror row_mask:0xf bank_mask:0xf
	v_add_u32_e32 v74, s0, v74
	s_and_saveexec_b64 s[0:1], vcc
	v_pk_add_f32 v[66:67], v[66:67], v[68:69]
	v_pk_add_f32 v[68:69], v[70:71], v[72:73]
	ds_write_b128 v74, v[66:69]
	s_or_b64 exec, exec, s[0:1]
	v_pk_mul_f32 v[70:71], v[60:61], v[60:61]
	v_pk_mul_f32 v[66:67], v[58:59], v[58:59]
	s_nop 1
	v_mov_b32_dpp v68, v66 quad_perm:[1,0,3,2] row_mask:0xf bank_mask:0xf
	v_mov_b32_dpp v69, v67 quad_perm:[1,0,3,2] row_mask:0xf bank_mask:0xf
	v_mov_b32_dpp v72, v70 quad_perm:[1,0,3,2] row_mask:0xf bank_mask:0xf
	v_mov_b32_dpp v73, v71 quad_perm:[1,0,3,2] row_mask:0xf bank_mask:0xf
	v_pk_fma_f32 v[66:67], v[58:59], v[58:59], v[68:69]
	v_pk_fma_f32 v[70:71], v[60:61], v[60:61], v[72:73]
	s_nop 0
	v_mov_b32_dpp v68, v66 quad_perm:[2,3,0,1] row_mask:0xf bank_mask:0xf
	v_mov_b32_dpp v69, v67 quad_perm:[2,3,0,1] row_mask:0xf bank_mask:0xf
	v_mov_b32_dpp v72, v70 quad_perm:[2,3,0,1] row_mask:0xf bank_mask:0xf
	v_mov_b32_dpp v73, v71 quad_perm:[2,3,0,1] row_mask:0xf bank_mask:0xf
	v_pk_add_f32 v[66:67], v[66:67], v[68:69]
	v_pk_add_f32 v[70:71], v[70:71], v[72:73]
	s_nop 0
	v_mov_b32_dpp v68, v66 row_half_mirror row_mask:0xf bank_mask:0xf
	v_mov_b32_dpp v69, v67 row_half_mirror row_mask:0xf bank_mask:0xf
	v_mov_b32_dpp v72, v70 row_half_mirror row_mask:0xf bank_mask:0xf
	v_mov_b32_dpp v73, v71 row_half_mirror row_mask:0xf bank_mask:0xf
	v_pk_add_f32 v[66:67], v[66:67], v[68:69]
	v_pk_add_f32 v[70:71], v[70:71], v[72:73]
	s_nop 0
	v_mov_b32_dpp v68, v66 row_mirror row_mask:0xf bank_mask:0xf
	v_mov_b32_dpp v69, v67 row_mirror row_mask:0xf bank_mask:0xf
	v_mov_b32_dpp v72, v70 row_mirror row_mask:0xf bank_mask:0xf
	v_mov_b32_dpp v73, v71 row_mirror row_mask:0xf bank_mask:0xf
	s_and_saveexec_b64 s[0:1], vcc
	v_pk_add_f32 v[66:67], v[66:67], v[68:69]
	v_pk_add_f32 v[68:69], v[70:71], v[72:73]
	ds_write_b128 v74, v[66:69] offset:64
	s_or_b64 exec, exec, s[0:1]
	v_pk_mul_f32 v[70:71], v[56:57], v[56:57]
	v_pk_mul_f32 v[66:67], v[54:55], v[54:55]
	s_nop 1
	v_mov_b32_dpp v68, v66 quad_perm:[1,0,3,2] row_mask:0xf bank_mask:0xf
	v_mov_b32_dpp v69, v67 quad_perm:[1,0,3,2] row_mask:0xf bank_mask:0xf
	v_mov_b32_dpp v72, v70 quad_perm:[1,0,3,2] row_mask:0xf bank_mask:0xf
	v_mov_b32_dpp v73, v71 quad_perm:[1,0,3,2] row_mask:0xf bank_mask:0xf
	v_pk_fma_f32 v[66:67], v[54:55], v[54:55], v[68:69]
	v_pk_fma_f32 v[70:71], v[56:57], v[56:57], v[72:73]
	s_nop 0
	v_mov_b32_dpp v68, v66 quad_perm:[2,3,0,1] row_mask:0xf bank_mask:0xf
	v_mov_b32_dpp v69, v67 quad_perm:[2,3,0,1] row_mask:0xf bank_mask:0xf
	v_mov_b32_dpp v72, v70 quad_perm:[2,3,0,1] row_mask:0xf bank_mask:0xf
	v_mov_b32_dpp v73, v71 quad_perm:[2,3,0,1] row_mask:0xf bank_mask:0xf
	v_pk_add_f32 v[66:67], v[66:67], v[68:69]
	v_pk_add_f32 v[70:71], v[70:71], v[72:73]
	s_nop 0
	v_mov_b32_dpp v68, v66 row_half_mirror row_mask:0xf bank_mask:0xf
	v_mov_b32_dpp v69, v67 row_half_mirror row_mask:0xf bank_mask:0xf
	v_mov_b32_dpp v72, v70 row_half_mirror row_mask:0xf bank_mask:0xf
	v_mov_b32_dpp v73, v71 row_half_mirror row_mask:0xf bank_mask:0xf
	v_pk_add_f32 v[66:67], v[66:67], v[68:69]
	v_pk_add_f32 v[70:71], v[70:71], v[72:73]
	s_nop 0
	v_mov_b32_dpp v68, v66 row_mirror row_mask:0xf bank_mask:0xf
	v_mov_b32_dpp v69, v67 row_mirror row_mask:0xf bank_mask:0xf
	v_mov_b32_dpp v72, v70 row_mirror row_mask:0xf bank_mask:0xf
	v_mov_b32_dpp v73, v71 row_mirror row_mask:0xf bank_mask:0xf
	s_and_saveexec_b64 s[0:1], vcc
	v_pk_add_f32 v[66:67], v[66:67], v[68:69]
	v_pk_add_f32 v[68:69], v[70:71], v[72:73]
	ds_write_b128 v74, v[66:69] offset:128
	s_or_b64 exec, exec, s[0:1]
	v_pk_mul_f32 v[70:71], v[52:53], v[52:53]
	v_pk_mul_f32 v[66:67], v[50:51], v[50:51]
	s_nop 1
	v_mov_b32_dpp v68, v66 quad_perm:[1,0,3,2] row_mask:0xf bank_mask:0xf
	v_mov_b32_dpp v69, v67 quad_perm:[1,0,3,2] row_mask:0xf bank_mask:0xf
	v_mov_b32_dpp v72, v70 quad_perm:[1,0,3,2] row_mask:0xf bank_mask:0xf
	v_mov_b32_dpp v73, v71 quad_perm:[1,0,3,2] row_mask:0xf bank_mask:0xf
	v_pk_fma_f32 v[66:67], v[50:51], v[50:51], v[68:69]
	v_pk_fma_f32 v[70:71], v[52:53], v[52:53], v[72:73]
	s_nop 0
; __device__ void gla_C(const Params& P, int l, int item, LAS unsigned char* lds) {
;     ...
;     {
; #pragma unroll
;         for (int rt = 0; rt < 16; ++rt) {
;             float sv[4];
; #pragma unroll
;             for (int jj = 0; jj < 4; ++jj) sv[jj] = O[rt][jj] * O[rt][jj];
; #pragma unroll
;             for (int jj = 0; jj < 4; ++jj) sv[jj] = dpp_row_sum16(sv[jj]);
;             if (c == 0) {
; #pragma unroll
;                 for (int jj = 0; jj < 4; ++jj) SSQ[w * 256 + rt * 16 + 4 * g + jj] = sv[jj]; }
;         }
;     }
	v_mov_b32_dpp v68, v66 quad_perm:[2,3,0,1] row_mask:0xf bank_mask:0xf
	v_mov_b32_dpp v69, v67 quad_perm:[2,3,0,1] row_mask:0xf bank_mask:0xf
	v_mov_b32_dpp v72, v70 quad_perm:[2,3,0,1] row_mask:0xf bank_mask:0xf
	v_mov_b32_dpp v73, v71 quad_perm:[2,3,0,1] row_mask:0xf bank_mask:0xf
	v_pk_add_f32 v[66:67], v[66:67], v[68:69]
	v_pk_add_f32 v[70:71], v[70:71], v[72:73]
	s_nop 0
	v_mov_b32_dpp v68, v66 row_half_mirror row_mask:0xf bank_mask:0xf
	v_mov_b32_dpp v69, v67 row_half_mirror row_mask:0xf bank_mask:0xf
	v_mov_b32_dpp v72, v70 row_half_mirror row_mask:0xf bank_mask:0xf
	v_mov_b32_dpp v73, v71 row_half_mirror row_mask:0xf bank_mask:0xf
	v_pk_add_f32 v[66:67], v[66:67], v[68:69]
	v_pk_add_f32 v[70:71], v[70:71], v[72:73]
	s_nop 0
	v_mov_b32_dpp v68, v66 row_mirror row_mask:0xf bank_mask:0xf
	v_mov_b32_dpp v69, v67 row_mirror row_mask:0xf bank_mask:0xf
	v_mov_b32_dpp v72, v70 row_mirror row_mask:0xf bank_mask:0xf
	v_mov_b32_dpp v73, v71 row_mirror row_mask:0xf bank_mask:0xf
	s_and_saveexec_b64 s[0:1], vcc
	v_pk_add_f32 v[66:67], v[66:67], v[68:69]
	v_pk_add_f32 v[68:69], v[70:71], v[72:73]
	ds_write_b128 v74, v[66:69] offset:192
	s_or_b64 exec, exec, s[0:1]
	v_pk_mul_f32 v[70:71], v[48:49], v[48:49]
	v_pk_mul_f32 v[66:67], v[46:47], v[46:47]
	s_nop 1
	v_mov_b32_dpp v68, v66 quad_perm:[1,0,3,2] row_mask:0xf bank_mask:0xf
	v_mov_b32_dpp v69, v67 quad_perm:[1,0,3,2] row_mask:0xf bank_mask:0xf
	v_mov_b32_dpp v72, v70 quad_perm:[1,0,3,2] row_mask:0xf bank_mask:0xf
	v_mov_b32_dpp v73, v71 quad_perm:[1,0,3,2] row_mask:0xf bank_mask:0xf
	v_pk_fma_f32 v[66:67], v[46:47], v[46:47], v[68:69]
	v_pk_fma_f32 v[70:71], v[48:49], v[48:49], v[72:73]
	s_nop 0
	v_mov_b32_dpp v68, v66 quad_perm:[2,3,0,1] row_mask:0xf bank_mask:0xf
	v_mov_b32_dpp v69, v67 quad_perm:[2,3,0,1] row_mask:0xf bank_mask:0xf
	v_mov_b32_dpp v72, v70 quad_perm:[2,3,0,1] row_mask:0xf bank_mask:0xf
	v_mov_b32_dpp v73, v71 quad_perm:[2,3,0,1] row_mask:0xf bank_mask:0xf
	v_pk_add_f32 v[66:67], v[66:67], v[68:69]
	v_pk_add_f32 v[70:71], v[70:71], v[72:73]
	s_nop 0
	v_mov_b32_dpp v68, v66 row_half_mirror row_mask:0xf bank_mask:0xf
	v_mov_b32_dpp v69, v67 row_half_mirror row_mask:0xf bank_mask:0xf
	v_mov_b32_dpp v72, v70 row_half_mirror row_mask:0xf bank_mask:0xf
	v_mov_b32_dpp v73, v71 row_half_mirror row_mask:0xf bank_mask:0xf
	v_pk_add_f32 v[66:67], v[66:67], v[68:69]
	v_pk_add_f32 v[70:71], v[70:71], v[72:73]
	s_nop 0
	v_mov_b32_dpp v68, v66 row_mirror row_mask:0xf bank_mask:0xf
	v_mov_b32_dpp v69, v67 row_mirror row_mask:0xf bank_mask:0xf
	v_mov_b32_dpp v72, v70 row_mirror row_mask:0xf bank_mask:0xf
	v_mov_b32_dpp v73, v71 row_mirror row_mask:0xf bank_mask:0xf
	s_and_saveexec_b64 s[0:1], vcc
	v_pk_add_f32 v[66:67], v[66:67], v[68:69]
	v_pk_add_f32 v[68:69], v[70:71], v[72:73]
	ds_write_b128 v74, v[66:69] offset:256
	s_or_b64 exec, exec, s[0:1]
	v_pk_mul_f32 v[70:71], v[44:45], v[44:45]
	v_pk_mul_f32 v[66:67], v[42:43], v[42:43]
	s_nop 1
	v_mov_b32_dpp v68, v66 quad_perm:[1,0,3,2] row_mask:0xf bank_mask:0xf
	v_mov_b32_dpp v69, v67 quad_perm:[1,0,3,2] row_mask:0xf bank_mask:0xf
	v_mov_b32_dpp v72, v70 quad_perm:[1,0,3,2] row_mask:0xf bank_mask:0xf
	v_mov_b32_dpp v73, v71 quad_perm:[1,0,3,2] row_mask:0xf bank_mask:0xf
	v_pk_fma_f32 v[66:67], v[42:43], v[42:43], v[68:69]
	v_pk_fma_f32 v[70:71], v[44:45], v[44:45], v[72:73]
	s_nop 0
	v_mov_b32_dpp v68, v66 quad_perm:[2,3,0,1] row_mask:0xf bank_mask:0xf
	v_mov_b32_dpp v69, v67 quad_perm:[2,3,0,1] row_mask:0xf bank_mask:0xf
	v_mov_b32_dpp v72, v70 quad_perm:[2,3,0,1] row_mask:0xf bank_mask:0xf
	v_mov_b32_dpp v73, v71 quad_perm:[2,3,0,1] row_mask:0xf bank_mask:0xf
	v_pk_add_f32 v[66:67], v[66:67], v[68:69]
	v_pk_add_f32 v[70:71], v[70:71], v[72:73]
	s_nop 0
	v_mov_b32_dpp v68, v66 row_half_mirror row_mask:0xf bank_mask:0xf
	v_mov_b32_dpp v69, v67 row_half_mirror row_mask:0xf bank_mask:0xf
	v_mov_b32_dpp v72, v70 row_half_mirror row_mask:0xf bank_mask:0xf
	v_mov_b32_dpp v73, v71 row_half_mirror row_mask:0xf bank_mask:0xf
	v_pk_add_f32 v[66:67], v[66:67], v[68:69]
	v_pk_add_f32 v[70:71], v[70:71], v[72:73]
	s_nop 0
	v_mov_b32_dpp v68, v66 row_mirror row_mask:0xf bank_mask:0xf
	v_mov_b32_dpp v69, v67 row_mirror row_mask:0xf bank_mask:0xf
	v_mov_b32_dpp v72, v70 row_mirror row_mask:0xf bank_mask:0xf
	v_mov_b32_dpp v73, v71 row_mirror row_mask:0xf bank_mask:0xf
	s_and_saveexec_b64 s[0:1], vcc
	v_pk_add_f32 v[66:67], v[66:67], v[68:69]
	v_pk_add_f32 v[68:69], v[70:71], v[72:73]
	ds_write_b128 v74, v[66:69] offset:320
	s_or_b64 exec, exec, s[0:1]
	v_pk_mul_f32 v[70:71], v[40:41], v[40:41]
	v_pk_mul_f32 v[66:67], v[38:39], v[38:39]
	s_nop 1
	v_mov_b32_dpp v68, v66 quad_perm:[1,0,3,2] row_mask:0xf bank_mask:0xf
	v_mov_b32_dpp v69, v67 quad_perm:[1,0,3,2] row_mask:0xf bank_mask:0xf
	v_mov_b32_dpp v72, v70 quad_perm:[1,0,3,2] row_mask:0xf bank_mask:0xf
	v_mov_b32_dpp v73, v71 quad_perm:[1,0,3,2] row_mask:0xf bank_mask:0xf
	v_pk_fma_f32 v[66:67], v[38:39], v[38:39], v[68:69]
	v_pk_fma_f32 v[70:71], v[40:41], v[40:41], v[72:73]
	s_nop 0
	v_mov_b32_dpp v68, v66 quad_perm:[2,3,0,1] row_mask:0xf bank_mask:0xf
	v_mov_b32_dpp v69, v67 quad_perm:[2,3,0,1] row_mask:0xf bank_mask:0xf
	v_mov_b32_dpp v72, v70 quad_perm:[2,3,0,1] row_mask:0xf bank_mask:0xf
	v_mov_b32_dpp v73, v71 quad_perm:[2,3,0,1] row_mask:0xf bank_mask:0xf
	v_pk_add_f32 v[66:67], v[66:67], v[68:69]
	v_pk_add_f32 v[70:71], v[70:71], v[72:73]
	s_nop 0
	v_mov_b32_dpp v68, v66 row_half_mirror row_mask:0xf bank_mask:0xf
	v_mov_b32_dpp v69, v67 row_half_mirror row_mask:0xf bank_mask:0xf
	v_mov_b32_dpp v72, v70 row_half_mirror row_mask:0xf bank_mask:0xf
	v_mov_b32_dpp v73, v71 row_half_mirror row_mask:0xf bank_mask:0xf
; __device__ void gla_C(const Params& P, int l, int item, LAS unsigned char* lds) {
;     ...
;     {
; #pragma unroll
;         for (int rt = 0; rt < 16; ++rt) {
;             float sv[4];
; #pragma unroll
;             for (int jj = 0; jj < 4; ++jj) sv[jj] = O[rt][jj] * O[rt][jj];
; #pragma unroll
;             for (int jj = 0; jj < 4; ++jj) sv[jj] = dpp_row_sum16(sv[jj]);
;             if (c == 0) {
; #pragma unroll
;                 for (int jj = 0; jj < 4; ++jj) SSQ[w * 256 + rt * 16 + 4 * g + jj] = sv[jj]; }
;         }
;     }
	v_pk_add_f32 v[66:67], v[66:67], v[68:69]
	v_pk_add_f32 v[70:71], v[70:71], v[72:73]
	s_nop 0
	v_mov_b32_dpp v68, v66 row_mirror row_mask:0xf bank_mask:0xf
	v_mov_b32_dpp v69, v67 row_mirror row_mask:0xf bank_mask:0xf
	v_mov_b32_dpp v72, v70 row_mirror row_mask:0xf bank_mask:0xf
	v_mov_b32_dpp v73, v71 row_mirror row_mask:0xf bank_mask:0xf
	s_and_saveexec_b64 s[0:1], vcc
	v_pk_add_f32 v[66:67], v[66:67], v[68:69]
	v_pk_add_f32 v[68:69], v[70:71], v[72:73]
	ds_write_b128 v74, v[66:69] offset:384
	s_or_b64 exec, exec, s[0:1]
	v_pk_mul_f32 v[70:71], v[36:37], v[36:37]
	v_pk_mul_f32 v[66:67], v[34:35], v[34:35]
	s_nop 1
	v_mov_b32_dpp v68, v66 quad_perm:[1,0,3,2] row_mask:0xf bank_mask:0xf
	v_mov_b32_dpp v69, v67 quad_perm:[1,0,3,2] row_mask:0xf bank_mask:0xf
	v_mov_b32_dpp v72, v70 quad_perm:[1,0,3,2] row_mask:0xf bank_mask:0xf
	v_mov_b32_dpp v73, v71 quad_perm:[1,0,3,2] row_mask:0xf bank_mask:0xf
	v_pk_fma_f32 v[66:67], v[34:35], v[34:35], v[68:69]
	v_pk_fma_f32 v[70:71], v[36:37], v[36:37], v[72:73]
	s_nop 0
	v_mov_b32_dpp v68, v66 quad_perm:[2,3,0,1] row_mask:0xf bank_mask:0xf
	v_mov_b32_dpp v69, v67 quad_perm:[2,3,0,1] row_mask:0xf bank_mask:0xf
	v_mov_b32_dpp v72, v70 quad_perm:[2,3,0,1] row_mask:0xf bank_mask:0xf
	v_mov_b32_dpp v73, v71 quad_perm:[2,3,0,1] row_mask:0xf bank_mask:0xf
	v_pk_add_f32 v[66:67], v[66:67], v[68:69]
	v_pk_add_f32 v[70:71], v[70:71], v[72:73]
	s_nop 0
	v_mov_b32_dpp v68, v66 row_half_mirror row_mask:0xf bank_mask:0xf
	v_mov_b32_dpp v69, v67 row_half_mirror row_mask:0xf bank_mask:0xf
	v_mov_b32_dpp v72, v70 row_half_mirror row_mask:0xf bank_mask:0xf
	v_mov_b32_dpp v73, v71 row_half_mirror row_mask:0xf bank_mask:0xf
	v_pk_add_f32 v[66:67], v[66:67], v[68:69]
	v_pk_add_f32 v[70:71], v[70:71], v[72:73]
	s_nop 0
	v_mov_b32_dpp v68, v66 row_mirror row_mask:0xf bank_mask:0xf
	v_mov_b32_dpp v69, v67 row_mirror row_mask:0xf bank_mask:0xf
	v_mov_b32_dpp v72, v70 row_mirror row_mask:0xf bank_mask:0xf
	v_mov_b32_dpp v73, v71 row_mirror row_mask:0xf bank_mask:0xf
	s_and_saveexec_b64 s[0:1], vcc
	v_pk_add_f32 v[66:67], v[66:67], v[68:69]
	v_pk_add_f32 v[68:69], v[70:71], v[72:73]
	ds_write_b128 v74, v[66:69] offset:448
	s_or_b64 exec, exec, s[0:1]
	v_pk_mul_f32 v[70:71], v[32:33], v[32:33]
	v_pk_mul_f32 v[66:67], v[30:31], v[30:31]
	s_nop 1
	v_mov_b32_dpp v68, v66 quad_perm:[1,0,3,2] row_mask:0xf bank_mask:0xf
	v_mov_b32_dpp v69, v67 quad_perm:[1,0,3,2] row_mask:0xf bank_mask:0xf
	v_mov_b32_dpp v72, v70 quad_perm:[1,0,3,2] row_mask:0xf bank_mask:0xf
	v_mov_b32_dpp v73, v71 quad_perm:[1,0,3,2] row_mask:0xf bank_mask:0xf
	v_pk_fma_f32 v[66:67], v[30:31], v[30:31], v[68:69]
	v_pk_fma_f32 v[70:71], v[32:33], v[32:33], v[72:73]
	s_nop 0
	v_mov_b32_dpp v68, v66 quad_perm:[2,3,0,1] row_mask:0xf bank_mask:0xf
	v_mov_b32_dpp v69, v67 quad_perm:[2,3,0,1] row_mask:0xf bank_mask:0xf
	v_mov_b32_dpp v72, v70 quad_perm:[2,3,0,1] row_mask:0xf bank_mask:0xf
	v_mov_b32_dpp v73, v71 quad_perm:[2,3,0,1] row_mask:0xf bank_mask:0xf
	v_pk_add_f32 v[66:67], v[66:67], v[68:69]
	v_pk_add_f32 v[70:71], v[70:71], v[72:73]
	s_nop 0
	v_mov_b32_dpp v68, v66 row_half_mirror row_mask:0xf bank_mask:0xf
	v_mov_b32_dpp v69, v67 row_half_mirror row_mask:0xf bank_mask:0xf
	v_mov_b32_dpp v72, v70 row_half_mirror row_mask:0xf bank_mask:0xf
	v_mov_b32_dpp v73, v71 row_half_mirror row_mask:0xf bank_mask:0xf
	v_pk_add_f32 v[66:67], v[66:67], v[68:69]
	v_pk_add_f32 v[70:71], v[70:71], v[72:73]
	s_nop 0
	v_mov_b32_dpp v68, v66 row_mirror row_mask:0xf bank_mask:0xf
	v_mov_b32_dpp v69, v67 row_mirror row_mask:0xf bank_mask:0xf
	v_mov_b32_dpp v72, v70 row_mirror row_mask:0xf bank_mask:0xf
	v_mov_b32_dpp v73, v71 row_mirror row_mask:0xf bank_mask:0xf
	s_and_saveexec_b64 s[0:1], vcc
	v_pk_add_f32 v[66:67], v[66:67], v[68:69]
	v_pk_add_f32 v[68:69], v[70:71], v[72:73]
	ds_write_b128 v74, v[66:69] offset:512
	s_or_b64 exec, exec, s[0:1]
	v_pk_mul_f32 v[70:71], v[28:29], v[28:29]
	v_pk_mul_f32 v[66:67], v[26:27], v[26:27]
	s_nop 1
	v_mov_b32_dpp v68, v66 quad_perm:[1,0,3,2] row_mask:0xf bank_mask:0xf
	v_mov_b32_dpp v69, v67 quad_perm:[1,0,3,2] row_mask:0xf bank_mask:0xf
	v_mov_b32_dpp v72, v70 quad_perm:[1,0,3,2] row_mask:0xf bank_mask:0xf
	v_mov_b32_dpp v73, v71 quad_perm:[1,0,3,2] row_mask:0xf bank_mask:0xf
	v_pk_fma_f32 v[66:67], v[26:27], v[26:27], v[68:69]
	v_pk_fma_f32 v[70:71], v[28:29], v[28:29], v[72:73]
	s_nop 0
	v_mov_b32_dpp v68, v66 quad_perm:[2,3,0,1] row_mask:0xf bank_mask:0xf
	v_mov_b32_dpp v69, v67 quad_perm:[2,3,0,1] row_mask:0xf bank_mask:0xf
	v_mov_b32_dpp v72, v70 quad_perm:[2,3,0,1] row_mask:0xf bank_mask:0xf
	v_mov_b32_dpp v73, v71 quad_perm:[2,3,0,1] row_mask:0xf bank_mask:0xf
	v_pk_add_f32 v[66:67], v[66:67], v[68:69]
	v_pk_add_f32 v[70:71], v[70:71], v[72:73]
	s_nop 0
	v_mov_b32_dpp v68, v66 row_half_mirror row_mask:0xf bank_mask:0xf
	v_mov_b32_dpp v69, v67 row_half_mirror row_mask:0xf bank_mask:0xf
	v_mov_b32_dpp v72, v70 row_half_mirror row_mask:0xf bank_mask:0xf
	v_mov_b32_dpp v73, v71 row_half_mirror row_mask:0xf bank_mask:0xf
	v_pk_add_f32 v[66:67], v[66:67], v[68:69]
	v_pk_add_f32 v[70:71], v[70:71], v[72:73]
	s_nop 0
	v_mov_b32_dpp v68, v66 row_mirror row_mask:0xf bank_mask:0xf
	v_mov_b32_dpp v69, v67 row_mirror row_mask:0xf bank_mask:0xf
	v_mov_b32_dpp v72, v70 row_mirror row_mask:0xf bank_mask:0xf
	v_mov_b32_dpp v73, v71 row_mirror row_mask:0xf bank_mask:0xf
	s_and_saveexec_b64 s[0:1], vcc
	v_pk_add_f32 v[66:67], v[66:67], v[68:69]
	v_pk_add_f32 v[68:69], v[70:71], v[72:73]
	ds_write_b128 v74, v[66:69] offset:576
	s_or_b64 exec, exec, s[0:1]
	v_pk_mul_f32 v[70:71], v[24:25], v[24:25]
	v_pk_mul_f32 v[66:67], v[22:23], v[22:23]
	s_nop 1
; __device__ void gla_C(const Params& P, int l, int item, LAS unsigned char* lds) {
;     ...
;     {
; #pragma unroll
;         for (int rt = 0; rt < 16; ++rt) {
;             float sv[4];
; #pragma unroll
;             for (int jj = 0; jj < 4; ++jj) sv[jj] = O[rt][jj] * O[rt][jj];
; #pragma unroll
;             for (int jj = 0; jj < 4; ++jj) sv[jj] = dpp_row_sum16(sv[jj]);
;             if (c == 0) {
; #pragma unroll
;                 for (int jj = 0; jj < 4; ++jj) SSQ[w * 256 + rt * 16 + 4 * g + jj] = sv[jj]; }
;         }
;     }
	v_mov_b32_dpp v68, v66 quad_perm:[1,0,3,2] row_mask:0xf bank_mask:0xf
	v_mov_b32_dpp v69, v67 quad_perm:[1,0,3,2] row_mask:0xf bank_mask:0xf
	v_mov_b32_dpp v72, v70 quad_perm:[1,0,3,2] row_mask:0xf bank_mask:0xf
	v_mov_b32_dpp v73, v71 quad_perm:[1,0,3,2] row_mask:0xf bank_mask:0xf
	v_pk_fma_f32 v[66:67], v[22:23], v[22:23], v[68:69]
	v_pk_fma_f32 v[70:71], v[24:25], v[24:25], v[72:73]
	s_nop 0
	v_mov_b32_dpp v68, v66 quad_perm:[2,3,0,1] row_mask:0xf bank_mask:0xf
	v_mov_b32_dpp v69, v67 quad_perm:[2,3,0,1] row_mask:0xf bank_mask:0xf
	v_mov_b32_dpp v72, v70 quad_perm:[2,3,0,1] row_mask:0xf bank_mask:0xf
	v_mov_b32_dpp v73, v71 quad_perm:[2,3,0,1] row_mask:0xf bank_mask:0xf
	v_pk_add_f32 v[66:67], v[66:67], v[68:69]
	v_pk_add_f32 v[70:71], v[70:71], v[72:73]
	s_nop 0
	v_mov_b32_dpp v68, v66 row_half_mirror row_mask:0xf bank_mask:0xf
	v_mov_b32_dpp v69, v67 row_half_mirror row_mask:0xf bank_mask:0xf
	v_mov_b32_dpp v72, v70 row_half_mirror row_mask:0xf bank_mask:0xf
	v_mov_b32_dpp v73, v71 row_half_mirror row_mask:0xf bank_mask:0xf
	v_pk_add_f32 v[66:67], v[66:67], v[68:69]
	v_pk_add_f32 v[70:71], v[70:71], v[72:73]
	s_nop 0
	v_mov_b32_dpp v68, v66 row_mirror row_mask:0xf bank_mask:0xf
	v_mov_b32_dpp v69, v67 row_mirror row_mask:0xf bank_mask:0xf
	v_mov_b32_dpp v72, v70 row_mirror row_mask:0xf bank_mask:0xf
	v_mov_b32_dpp v73, v71 row_mirror row_mask:0xf bank_mask:0xf
	s_and_saveexec_b64 s[0:1], vcc
	v_pk_add_f32 v[66:67], v[66:67], v[68:69]
	v_pk_add_f32 v[68:69], v[70:71], v[72:73]
	ds_write_b128 v74, v[66:69] offset:640
	s_or_b64 exec, exec, s[0:1]
	v_pk_mul_f32 v[70:71], v[20:21], v[20:21]
	v_pk_mul_f32 v[66:67], v[18:19], v[18:19]
	s_nop 1
	v_mov_b32_dpp v68, v66 quad_perm:[1,0,3,2] row_mask:0xf bank_mask:0xf
	v_mov_b32_dpp v69, v67 quad_perm:[1,0,3,2] row_mask:0xf bank_mask:0xf
	v_mov_b32_dpp v72, v70 quad_perm:[1,0,3,2] row_mask:0xf bank_mask:0xf
	v_mov_b32_dpp v73, v71 quad_perm:[1,0,3,2] row_mask:0xf bank_mask:0xf
	v_pk_fma_f32 v[66:67], v[18:19], v[18:19], v[68:69]
	v_pk_fma_f32 v[70:71], v[20:21], v[20:21], v[72:73]
	s_nop 0
	v_mov_b32_dpp v68, v66 quad_perm:[2,3,0,1] row_mask:0xf bank_mask:0xf
	v_mov_b32_dpp v69, v67 quad_perm:[2,3,0,1] row_mask:0xf bank_mask:0xf
	v_mov_b32_dpp v72, v70 quad_perm:[2,3,0,1] row_mask:0xf bank_mask:0xf
	v_mov_b32_dpp v73, v71 quad_perm:[2,3,0,1] row_mask:0xf bank_mask:0xf
	v_pk_add_f32 v[66:67], v[66:67], v[68:69]
	v_pk_add_f32 v[70:71], v[70:71], v[72:73]
	s_nop 0
	v_mov_b32_dpp v68, v66 row_half_mirror row_mask:0xf bank_mask:0xf
	v_mov_b32_dpp v69, v67 row_half_mirror row_mask:0xf bank_mask:0xf
	v_mov_b32_dpp v72, v70 row_half_mirror row_mask:0xf bank_mask:0xf
	v_mov_b32_dpp v73, v71 row_half_mirror row_mask:0xf bank_mask:0xf
	v_pk_add_f32 v[66:67], v[66:67], v[68:69]
	v_pk_add_f32 v[70:71], v[70:71], v[72:73]
	s_nop 0
	v_mov_b32_dpp v68, v66 row_mirror row_mask:0xf bank_mask:0xf
	v_mov_b32_dpp v69, v67 row_mirror row_mask:0xf bank_mask:0xf
	v_mov_b32_dpp v72, v70 row_mirror row_mask:0xf bank_mask:0xf
	v_mov_b32_dpp v73, v71 row_mirror row_mask:0xf bank_mask:0xf
	s_and_saveexec_b64 s[0:1], vcc
	v_pk_add_f32 v[66:67], v[66:67], v[68:69]
	v_pk_add_f32 v[68:69], v[70:71], v[72:73]
	ds_write_b128 v74, v[66:69] offset:704
	s_or_b64 exec, exec, s[0:1]
	v_pk_mul_f32 v[70:71], v[16:17], v[16:17]
	v_pk_mul_f32 v[66:67], v[14:15], v[14:15]
	s_nop 1
	v_mov_b32_dpp v68, v66 quad_perm:[1,0,3,2] row_mask:0xf bank_mask:0xf
	v_mov_b32_dpp v69, v67 quad_perm:[1,0,3,2] row_mask:0xf bank_mask:0xf
	v_mov_b32_dpp v72, v70 quad_perm:[1,0,3,2] row_mask:0xf bank_mask:0xf
	v_mov_b32_dpp v73, v71 quad_perm:[1,0,3,2] row_mask:0xf bank_mask:0xf
	v_pk_fma_f32 v[66:67], v[14:15], v[14:15], v[68:69]
	v_pk_fma_f32 v[70:71], v[16:17], v[16:17], v[72:73]
	s_nop 0
	v_mov_b32_dpp v68, v66 quad_perm:[2,3,0,1] row_mask:0xf bank_mask:0xf
	v_mov_b32_dpp v69, v67 quad_perm:[2,3,0,1] row_mask:0xf bank_mask:0xf
	v_mov_b32_dpp v72, v70 quad_perm:[2,3,0,1] row_mask:0xf bank_mask:0xf
	v_mov_b32_dpp v73, v71 quad_perm:[2,3,0,1] row_mask:0xf bank_mask:0xf
	v_pk_add_f32 v[66:67], v[66:67], v[68:69]
	v_pk_add_f32 v[70:71], v[70:71], v[72:73]
	s_nop 0
	v_mov_b32_dpp v68, v66 row_half_mirror row_mask:0xf bank_mask:0xf
	v_mov_b32_dpp v69, v67 row_half_mirror row_mask:0xf bank_mask:0xf
	v_mov_b32_dpp v72, v70 row_half_mirror row_mask:0xf bank_mask:0xf
	v_mov_b32_dpp v73, v71 row_half_mirror row_mask:0xf bank_mask:0xf
	v_pk_add_f32 v[66:67], v[66:67], v[68:69]
	v_pk_add_f32 v[70:71], v[70:71], v[72:73]
	s_nop 0
	v_mov_b32_dpp v68, v66 row_mirror row_mask:0xf bank_mask:0xf
	v_mov_b32_dpp v69, v67 row_mirror row_mask:0xf bank_mask:0xf
	v_mov_b32_dpp v72, v70 row_mirror row_mask:0xf bank_mask:0xf
	v_mov_b32_dpp v73, v71 row_mirror row_mask:0xf bank_mask:0xf
	s_and_saveexec_b64 s[0:1], vcc
	v_pk_add_f32 v[66:67], v[66:67], v[68:69]
	v_pk_add_f32 v[68:69], v[70:71], v[72:73]
	ds_write_b128 v74, v[66:69] offset:768
	s_or_b64 exec, exec, s[0:1]
	v_pk_mul_f32 v[70:71], v[12:13], v[12:13]
; __device__ void gla_C(const Params& P, int l, int item, LAS unsigned char* lds) {
;     ...
;     {
; #pragma unroll
;         for (int rt = 0; rt < 16; ++rt) {
;             float sv[4];
; #pragma unroll
;             for (int jj = 0; jj < 4; ++jj) sv[jj] = O[rt][jj] * O[rt][jj];
; #pragma unroll
;             for (int jj = 0; jj < 4; ++jj) sv[jj] = dpp_row_sum16(sv[jj]);
;             if (c == 0) {
; #pragma unroll
;                 for (int jj = 0; jj < 4; ++jj) SSQ[w * 256 + rt * 16 + 4 * g + jj] = sv[jj]; }
;         }
;     }
	v_pk_mul_f32 v[66:67], v[10:11], v[10:11]
	s_nop 1
	v_mov_b32_dpp v68, v66 quad_perm:[1,0,3,2] row_mask:0xf bank_mask:0xf
	v_mov_b32_dpp v69, v67 quad_perm:[1,0,3,2] row_mask:0xf bank_mask:0xf
	v_mov_b32_dpp v72, v70 quad_perm:[1,0,3,2] row_mask:0xf bank_mask:0xf
	v_mov_b32_dpp v73, v71 quad_perm:[1,0,3,2] row_mask:0xf bank_mask:0xf
	v_pk_fma_f32 v[66:67], v[10:11], v[10:11], v[68:69]
	v_pk_fma_f32 v[70:71], v[12:13], v[12:13], v[72:73]
	s_nop 0
	v_mov_b32_dpp v68, v66 quad_perm:[2,3,0,1] row_mask:0xf bank_mask:0xf
	v_mov_b32_dpp v69, v67 quad_perm:[2,3,0,1] row_mask:0xf bank_mask:0xf
	v_mov_b32_dpp v72, v70 quad_perm:[2,3,0,1] row_mask:0xf bank_mask:0xf
	v_mov_b32_dpp v73, v71 quad_perm:[2,3,0,1] row_mask:0xf bank_mask:0xf
	v_pk_add_f32 v[66:67], v[66:67], v[68:69]
	v_pk_add_f32 v[70:71], v[70:71], v[72:73]
	s_nop 0
	v_mov_b32_dpp v68, v66 row_half_mirror row_mask:0xf bank_mask:0xf
	v_mov_b32_dpp v69, v67 row_half_mirror row_mask:0xf bank_mask:0xf
	v_mov_b32_dpp v72, v70 row_half_mirror row_mask:0xf bank_mask:0xf
	v_mov_b32_dpp v73, v71 row_half_mirror row_mask:0xf bank_mask:0xf
	v_pk_add_f32 v[66:67], v[66:67], v[68:69]
	v_pk_add_f32 v[70:71], v[70:71], v[72:73]
	s_nop 0
	v_mov_b32_dpp v68, v66 row_mirror row_mask:0xf bank_mask:0xf
	v_mov_b32_dpp v69, v67 row_mirror row_mask:0xf bank_mask:0xf
	v_mov_b32_dpp v72, v70 row_mirror row_mask:0xf bank_mask:0xf
	v_mov_b32_dpp v73, v71 row_mirror row_mask:0xf bank_mask:0xf
	s_and_saveexec_b64 s[0:1], vcc
	v_pk_add_f32 v[66:67], v[66:67], v[68:69]
	v_pk_add_f32 v[68:69], v[70:71], v[72:73]
	ds_write_b128 v74, v[66:69] offset:832
	s_or_b64 exec, exec, s[0:1]
	v_pk_mul_f32 v[70:71], v[8:9], v[8:9]
	v_pk_mul_f32 v[66:67], v[6:7], v[6:7]
	s_nop 1
	v_mov_b32_dpp v68, v66 quad_perm:[1,0,3,2] row_mask:0xf bank_mask:0xf
	v_mov_b32_dpp v69, v67 quad_perm:[1,0,3,2] row_mask:0xf bank_mask:0xf
	v_mov_b32_dpp v72, v70 quad_perm:[1,0,3,2] row_mask:0xf bank_mask:0xf
	v_mov_b32_dpp v73, v71 quad_perm:[1,0,3,2] row_mask:0xf bank_mask:0xf
	v_pk_fma_f32 v[66:67], v[6:7], v[6:7], v[68:69]
	v_pk_fma_f32 v[70:71], v[8:9], v[8:9], v[72:73]
	s_nop 0
	v_mov_b32_dpp v68, v66 quad_perm:[2,3,0,1] row_mask:0xf bank_mask:0xf
	v_mov_b32_dpp v69, v67 quad_perm:[2,3,0,1] row_mask:0xf bank_mask:0xf
	v_mov_b32_dpp v72, v70 quad_perm:[2,3,0,1] row_mask:0xf bank_mask:0xf
	v_mov_b32_dpp v73, v71 quad_perm:[2,3,0,1] row_mask:0xf bank_mask:0xf
	v_pk_add_f32 v[66:67], v[66:67], v[68:69]
	v_pk_add_f32 v[70:71], v[70:71], v[72:73]
	s_nop 0
	v_mov_b32_dpp v68, v66 row_half_mirror row_mask:0xf bank_mask:0xf
	v_mov_b32_dpp v69, v67 row_half_mirror row_mask:0xf bank_mask:0xf
	v_mov_b32_dpp v72, v70 row_half_mirror row_mask:0xf bank_mask:0xf
	v_mov_b32_dpp v73, v71 row_half_mirror row_mask:0xf bank_mask:0xf
	v_pk_add_f32 v[66:67], v[66:67], v[68:69]
	v_pk_add_f32 v[70:71], v[70:71], v[72:73]
	s_nop 0
	v_mov_b32_dpp v68, v66 row_mirror row_mask:0xf bank_mask:0xf
	v_mov_b32_dpp v69, v67 row_mirror row_mask:0xf bank_mask:0xf
	v_mov_b32_dpp v72, v70 row_mirror row_mask:0xf bank_mask:0xf
	v_mov_b32_dpp v73, v71 row_mirror row_mask:0xf bank_mask:0xf
	s_and_saveexec_b64 s[0:1], vcc
	v_pk_add_f32 v[66:67], v[66:67], v[68:69]
	v_pk_add_f32 v[68:69], v[70:71], v[72:73]
	ds_write_b128 v74, v[66:69] offset:896
	s_or_b64 exec, exec, s[0:1]
	v_pk_mul_f32 v[70:71], v[4:5], v[4:5]
	v_pk_mul_f32 v[66:67], v[2:3], v[2:3]
	s_nop 1
	v_mov_b32_dpp v68, v66 quad_perm:[1,0,3,2] row_mask:0xf bank_mask:0xf
	v_mov_b32_dpp v69, v67 quad_perm:[1,0,3,2] row_mask:0xf bank_mask:0xf
	v_mov_b32_dpp v72, v70 quad_perm:[1,0,3,2] row_mask:0xf bank_mask:0xf
	v_mov_b32_dpp v73, v71 quad_perm:[1,0,3,2] row_mask:0xf bank_mask:0xf
	v_pk_fma_f32 v[66:67], v[2:3], v[2:3], v[68:69]
	v_pk_fma_f32 v[70:71], v[4:5], v[4:5], v[72:73]
	s_nop 0
	v_mov_b32_dpp v68, v66 quad_perm:[2,3,0,1] row_mask:0xf bank_mask:0xf
	v_mov_b32_dpp v69, v67 quad_perm:[2,3,0,1] row_mask:0xf bank_mask:0xf
	v_mov_b32_dpp v72, v70 quad_perm:[2,3,0,1] row_mask:0xf bank_mask:0xf
	v_mov_b32_dpp v73, v71 quad_perm:[2,3,0,1] row_mask:0xf bank_mask:0xf
	v_pk_add_f32 v[66:67], v[66:67], v[68:69]
	v_pk_add_f32 v[70:71], v[70:71], v[72:73]
	s_nop 0
	v_mov_b32_dpp v68, v66 row_half_mirror row_mask:0xf bank_mask:0xf
	v_mov_b32_dpp v69, v67 row_half_mirror row_mask:0xf bank_mask:0xf
	v_mov_b32_dpp v72, v70 row_half_mirror row_mask:0xf bank_mask:0xf
	v_mov_b32_dpp v73, v71 row_half_mirror row_mask:0xf bank_mask:0xf
	v_pk_add_f32 v[66:67], v[66:67], v[68:69]
	v_pk_add_f32 v[70:71], v[70:71], v[72:73]
	s_nop 0
	v_mov_b32_dpp v68, v66 row_mirror row_mask:0xf bank_mask:0xf
	v_mov_b32_dpp v69, v67 row_mirror row_mask:0xf bank_mask:0xf
	v_mov_b32_dpp v72, v70 row_mirror row_mask:0xf bank_mask:0xf
	v_mov_b32_dpp v73, v71 row_mirror row_mask:0xf bank_mask:0xf
	s_and_saveexec_b64 s[0:1], vcc
	s_cbranch_execz .LBB0_372
	v_pk_add_f32 v[66:67], v[66:67], v[68:69]
	v_pk_add_f32 v[68:69], v[70:71], v[72:73]
	ds_write_b128 v74, v[66:69] offset:960
	s_branch .LBB0_372

; #define LAS __attribute__((address_space(3)))
; __device__ __forceinline__ int get_tid() { int t = threadIdx.x; asm volatile("" : "+v"(t)); return t; }
; __device__ __forceinline__ void attn_item(const Params& P, int half, int item, LAS unsigned char* lds, unsigned* ctr) {
;     const int tid = get_tid(), lane = tid & 63, w = __builtin_amdgcn_readfirstlane(tid >> 6), g = lane >> 4, c = lane & 15;
;     const int b = item / 192, rem = item % 192, gi = rem / 64, r2 = rem % 64;
;     const int dil = (gi == 0) ? 1 : (gi == 1 ? 4 : 16), nb = 16 / dil;
;     const int n = r2 % nb, t2 = r2 / nb, hh = t2 & 3, rr = t2 >> 2;
;     bf16_t* Z = (bf16_t*)(P.ws + WS_Z);
;     const float* RC = (const float*)(P.ws + WS_RC); const float* RS = (const float*)(P.ws + WS_RS);
;     float* LSE = (float*)(P.ws + WS_LSE);
;     const int colq = ZDQ + gi * 512 + hh * 128, colk = ZDK + gi * 512 + hh * 128, colv = ZDV + gi * 512 + hh * 128;
;     const int rowb = b * 2048, gtb = half * TH;
;     constexpr int KSTR = 272, VSTR = 528;
;     LAS unsigned char* Ks = lds; LAS unsigned char* Vt = lds + 256 * KSTR;
;     constexpr float QSCALE = 0.08838834764831845f * 1.4426950408889634f;
;     const int km = tid >> 1, khf = tid & 1, klk = (n - 1) * 128 + km;
;     const int vkb = tid & 31, vdb = tid >> 5, vlk0 = (n - 1) * 128 + vkb * 8;
;     const int qi = 16 * w + c, qrow = rowb + (n * 128 + qi) * dil + rr;
;     u32x4 kx1[4], kx2[4]; f32x4 kinv[8]; float kpos = 0.f;
;     u32x4 rv[8];
;     u32x4 qx1[2], qx2[2]; f32x4 qinv[4]; float qpos;
;     if (klk >= 0) {
;         const int krow = rowb + klk * dil + rr;
;         const bf16_t* kp = Z + (size_t)krow * ZC + colk + khf * 32;
;         kpos = (float)P.pos[gtb + krow];
; #pragma unroll
;         for (int cc = 0; cc < 4; ++cc) { kx1[cc] = *(const u32x4*)(kp + cc * 8); kx2[cc] = *(const u32x4*)(kp + 64 + cc * 8);
;             kinv[2 * cc] = *(const f32x4*)(RC + khf * 32 + cc * 8); kinv[2 * cc + 1] = *(const f32x4*)(RC + khf * 32 + cc * 8 + 4); }
;     } else {
; #pragma unroll
;         for (int cc = 0; cc < 4; ++cc) { kx1[cc] = (u32x4){0u, 0u, 0u, 0u}; kx2[cc] = (u32x4){0u, 0u, 0u, 0u};
;             kinv[2 * cc] = (f32x4){0.f, 0.f, 0.f, 0.f}; kinv[2 * cc + 1] = (f32x4){0.f, 0.f, 0.f, 0.f}; }
;     }
.LBB0_528:
	s_and_b64 vcc, exec, s[30:31]
	s_cbranch_vccz .LBB0_517
	s_mul_hi_i32 s4, s2, 0x2aaaaaab
	s_lshr_b32 s5, s4, 31
	s_ashr_i32 s4, s4, 5
	s_add_i32 s10, s4, s5
	s_mul_i32 s4, s10, 0xc0
	s_sub_i32 s4, s2, s4
	s_lshr_b32 s2, s4, 25
	s_and_b32 s2, s2, 63
	s_add_i32 s5, s4, s2
	s_sext_i32_i16 s2, s5
	s_and_b32 s5, s5, 0xffc0
	s_ashr_i32 s2, s2, 6
	s_sub_i32 s8, s4, s5
	s_add_i32 s5, s4, 63
	s_andn2_b32 s4, s4, 63
	s_cmp_eq_u32 s4, 64
	s_cselect_b32 s4, 4, 1
	s_cselect_b32 s7, 2, 4
	s_cmpk_lt_u32 s5, 0x7f
	s_cselect_b32 s9, 16, s4
	s_sext_i32_i8 s11, s9
	v_cvt_f32_i32_e32 v2, s11
	s_sext_i32_i8 s12, s8
	v_cvt_f32_i32_e32 v3, s12
	s_cselect_b32 s7, 0, s7
	v_rcp_iflag_f32_e32 v4, v2
	s_xor_b32 s11, s12, s11
	s_ashr_i32 s11, s11, 30
	s_or_b32 s11, s11, 1
	v_mul_f32_e32 v4, v3, v4
	v_trunc_f32_e32 v4, v4
	v_fma_f32 v3, -v4, v2, v3
	v_cvt_i32_f32_e32 v4, v4
	v_cmp_ge_f32_e64 s[4:5], |v3|, |v2|
	s_and_b64 s[4:5], s[4:5], exec
	s_cselect_b32 s4, s11, 0
	v_readfirstlane_b32 s5, v4
	s_add_i32 s4, s5, s4
	s_sext_i32_i8 s11, s4
	s_mul_i32 s4, s4, s9
	s_sub_i32 s5, s8, s4
	s_sext_i32_i8 s12, s5
	v_mov_b32_e32 v137, v0
	s_lshl_b32 s13, s10, 11
	s_lshl_b32 s10, s12, 7
	s_add_i32 s12, s10, 0xffffff80
	v_ashrrev_i32_e32 v142, 1, v137
	s_and_b32 s4, s11, 3
	s_ashr_i32 s11, s11, 2
	v_and_b32_e32 v18, 1, v137
	v_add_u32_e32 v19, s12, v142
	v_readfirstlane_b32 s6, v137
	s_lshl_b32 s8, s2, 9
	s_lshl_b32 s9, s4, 7
	s_add_i32 s11, s11, s13
	v_cmp_lt_i32_e32 vcc, -1, v19
	v_lshlrev_b32_e32 v134, 6, v18
	s_waitcnt vmcnt(3)
	s_cmp_eq_u64 vcc, exec
	s_cbranch_scc1 .Lattn_kz_skip
	v_mov_b32_e32 v114, 0
	v_mov_b32_e32 v139, 0
	v_mov_b32_e32 v118, 0
	v_mov_b32_e32 v119, 0
	v_mov_b32_e32 v120, 0
	v_mov_b32_e32 v121, 0
	v_mov_b32_e32 v122, 0
	v_mov_b32_e32 v123, 0
	v_mov_b32_e32 v124, 0
	v_mov_b32_e32 v125, 0
	v_mov_b32_e32 v82, 0
	v_mov_b32_e32 v83, 0
	v_mov_b32_e32 v84, 0
	v_mov_b32_e32 v85, 0
	v_mov_b32_e32 v86, 0
	v_mov_b32_e32 v87, 0
	v_mov_b32_e32 v88, 0
	v_mov_b32_e32 v89, 0
	v_mov_b32_e32 v38, 0
	v_mov_b32_e32 v39, 0
	v_mov_b32_e32 v40, 0
	v_mov_b32_e32 v41, 0
	v_mov_b32_e32 v46, 0
	v_mov_b32_e32 v47, 0
	v_mov_b32_e32 v48, 0
	v_mov_b32_e32 v49, 0
	v_mov_b32_e32 v2, 0
	v_mov_b32_e32 v3, 0
	v_mov_b32_e32 v4, 0
	v_mov_b32_e32 v5, 0
	v_mov_b32_e32 v10, 0
	v_mov_b32_e32 v11, 0
	v_mov_b32_e32 v12, 0
	v_mov_b32_e32 v13, 0
	v_mov_b32_e32 v115, 0
	v_mov_b32_e32 v116, 0
	v_mov_b32_e32 v117, 0
	v_mov_b32_e32 v98, 0
	v_mov_b32_e32 v99, 0
	v_mov_b32_e32 v100, 0
	v_mov_b32_e32 v101, 0
	v_mov_b32_e32 v62, 0
	v_mov_b32_e32 v63, 0
	v_mov_b32_e32 v64, 0
	v_mov_b32_e32 v65, 0
	v_mov_b32_e32 v6, 0
	v_mov_b32_e32 v7, 0
	v_mov_b32_e32 v8, 0
	v_mov_b32_e32 v9, 0
	v_mov_b32_e32 v126, 0
	v_mov_b32_e32 v127, 0
	v_mov_b32_e32 v128, 0
	v_mov_b32_e32 v129, 0
	v_mov_b32_e32 v102, 0
	v_mov_b32_e32 v103, 0
	v_mov_b32_e32 v104, 0
	v_mov_b32_e32 v105, 0
	v_mov_b32_e32 v66, 0
	v_mov_b32_e32 v67, 0
	v_mov_b32_e32 v68, 0
	v_mov_b32_e32 v69, 0
	v_mov_b32_e32 v14, 0
	v_mov_b32_e32 v15, 0
	v_mov_b32_e32 v16, 0
	v_mov_b32_e32 v17, 0
; __device__ __forceinline__ void attn_item(const Params& P, int half, int item, LAS unsigned char* lds, unsigned* ctr) {
;     ...
;     if (klk >= 0) {
;         const int krow = rowb + klk * dil + rr;
;         const bf16_t* kp = Z + (size_t)krow * ZC + colk + khf * 32;
;         kpos = (float)P.pos[gtb + krow];
; #pragma unroll
;         for (int cc = 0; cc < 4; ++cc) { kx1[cc] = *(const u32x4*)(kp + cc * 8); kx2[cc] = *(const u32x4*)(kp + 64 + cc * 8);
;             kinv[2 * cc] = *(const f32x4*)(RC + khf * 32 + cc * 8); kinv[2 * cc + 1] = *(const f32x4*)(RC + khf * 32 + cc * 8 + 4); }
;     } else {
; #pragma unroll
;         for (int cc = 0; cc < 4; ++cc) { kx1[cc] = (u32x4){0u, 0u, 0u, 0u}; kx2[cc] = (u32x4){0u, 0u, 0u, 0u};
;             kinv[2 * cc] = (f32x4){0.f, 0.f, 0.f, 0.f}; kinv[2 * cc + 1] = (f32x4){0.f, 0.f, 0.f, 0.f}; }
;     }
;     if (vlk0 >= 0) {
; #pragma unroll
;         for (int kk = 0; kk < 8; ++kk) { const int row = rowb + (vlk0 + kk) * dil + rr; rv[kk] = *(const u32x4*)(Z + (size_t)row * ZC + colv + vdb * 8); }
;     } else {
; #pragma unroll
;         for (int kk = 0; kk < 8; ++kk) rv[kk] = (u32x4){0u, 0u, 0u, 0u};
;     }
.Lattn_kz_skip:
	s_and_saveexec_b64 s[30:31], vcc
	s_cbranch_execz .LBB0_531
	v_lshlrev_b32_e32 v2, s7, v19
	s_add_i32 s13, s8, s9
	v_add_u32_e32 v4, s11, v2
	v_mov_b64_e32 v[2:3], s[28:29]
	s_add_i32 s20, s13, 0x1200
	v_mad_i64_i32 v[2:3], s[14:15], v4, s25, v[2:3]
	v_add_u32_e32 v4, s44, v4
	v_readlane_b32 s48, v252, 9
	v_lshl_add_u64 v[2:3], s[20:21], 1, v[2:3]
	v_mov_b32_e32 v135, v195
	v_ashrrev_i32_e32 v5, 31, v4
	v_readlane_b32 s50, v252, 11
	v_readlane_b32 s51, v252, 12
	v_readlane_b32 s14, v251, 35
	v_lshl_add_u64 v[2:3], v[2:3], 0, v[134:135]
	v_lshl_add_u64 v[4:5], v[4:5], 2, s[50:51]
	v_lshlrev_b32_e32 v10, 7, v18
	v_readlane_b32 s15, v251, 36
	global_load_dword v19, v[4:5], off
	global_load_dwordx4 v[126:129], v[2:3], off
	global_load_dwordx4 v[102:105], v[2:3], off offset:16
	global_load_dwordx4 v[66:69], v[2:3], off offset:32
	global_load_dwordx4 v[14:17], v[2:3], off offset:48
	global_load_dwordx4 v[114:117], v[2:3], off offset:128
	global_load_dwordx4 v[98:101], v[2:3], off offset:144
	global_load_dwordx4 v[62:65], v[2:3], off offset:160
	global_load_dwordx4 v[6:9], v[2:3], off offset:176
	global_load_dwordx4 v[118:121], v10, s[14:15]
	global_load_dwordx4 v[122:125], v10, s[14:15] offset:16
	global_load_dwordx4 v[82:85], v10, s[14:15] offset:32
	global_load_dwordx4 v[86:89], v10, s[14:15] offset:48
	global_load_dwordx4 v[38:41], v10, s[14:15] offset:64
	global_load_dwordx4 v[46:49], v10, s[14:15] offset:80
	global_load_dwordx4 v[2:5], v10, s[14:15] offset:96
	s_nop 0
	global_load_dwordx4 v[10:13], v10, s[14:15] offset:112
	v_readlane_b32 s49, v252, 10
	v_readlane_b32 s52, v252, 13
	v_readlane_b32 s53, v252, 14
	v_readlane_b32 s54, v252, 15
	v_readlane_b32 s55, v252, 16
	v_readlane_b32 s56, v252, 17
	v_readlane_b32 s57, v252, 18
	v_readlane_b32 s58, v252, 19
	v_readlane_b32 s59, v252, 20
	v_readlane_b32 s60, v252, 21
	v_readlane_b32 s61, v252, 22
	v_readlane_b32 s62, v252, 23
	v_readlane_b32 s63, v252, 24
	s_waitcnt vmcnt(16)
	v_cvt_f32_i32_e32 v139, v19
.LBB0_531:
	s_or_b64 exec, exec, s[30:31]
	v_and_b32_e32 v140, 31, v137
	v_ashrrev_i32_e32 v18, 5, v137
	v_lshl_add_u32 v42, v140, 3, s12
	v_cmp_gt_i32_e32 vcc, 0, v42
	v_lshlrev_b32_e32 v132, 3, v18
	s_and_saveexec_b64 s[12:13], vcc
	s_xor_b64 s[30:31], exec, s[12:13]
	v_lshlrev_b32_e32 v132, 3, v18
	s_or_saveexec_b64 s[30:31], s[30:31]
	v_mov_b32_e32 v135, 0
	s_cmp_eq_u64 s[30:31], 0
	s_cbranch_scc1 .Lattn_vz_skip
	v_mov_b32_e32 v34, 0
	v_mov_b32_e32 v35, 0
	v_mov_b32_e32 v36, 0
	v_mov_b32_e32 v37, 0
	v_mov_b32_e32 v18, 0
	v_mov_b32_e32 v19, 0
	v_mov_b32_e32 v20, 0
	v_mov_b32_e32 v21, 0
	v_mov_b32_e32 v22, 0
	v_mov_b32_e32 v23, 0
	v_mov_b32_e32 v24, 0
	v_mov_b32_e32 v25, 0
	v_mov_b32_e32 v26, 0
	v_mov_b32_e32 v27, 0
	v_mov_b32_e32 v28, 0
	v_mov_b32_e32 v29, 0
	v_mov_b32_e32 v30, 0
	v_mov_b32_e32 v31, 0
	v_mov_b32_e32 v32, 0
	v_mov_b32_e32 v33, 0
	v_mov_b32_e32 v50, 0
	v_mov_b32_e32 v51, 0
	v_mov_b32_e32 v52, 0
	v_mov_b32_e32 v53, 0
	v_mov_b32_e32 v58, 0
	v_mov_b32_e32 v59, 0
	v_mov_b32_e32 v60, 0
	v_mov_b32_e32 v61, 0
	v_mov_b32_e32 v70, 0
	v_mov_b32_e32 v71, 0
	v_mov_b32_e32 v72, 0
	v_mov_b32_e32 v73, 0
.Lattn_vz_skip:
	s_xor_b64 exec, exec, s[30:31]
	s_cbranch_execz .LBB0_535
	s_add_i32 s12, s8, s9
	s_add_i32 s20, s12, 0x1800
	s_lshl_b64 s[12:13], s[20:21], 1
	s_add_u32 s12, s28, s12
	v_or_b32_e32 v20, 1, v42
	v_or_b32_e32 v26, 2, v42
	v_or_b32_e32 v28, 3, v42
	v_or_b32_e32 v36, 4, v42
	s_addc_u32 s13, s29, s13
	v_ashrrev_i32_e32 v133, 31, v132
	v_lshlrev_b32_e32 v18, s7, v42
	v_lshlrev_b32_e32 v20, s7, v20
	v_lshlrev_b32_e32 v26, s7, v26
	v_lshlrev_b32_e32 v28, s7, v28
	v_lshlrev_b32_e32 v36, s7, v36
	v_or_b32_e32 v43, 5, v42
	v_lshl_add_u64 v[34:35], v[132:133], 1, s[12:13]
	v_add_u32_e32 v18, s11, v18
	v_add_u32_e32 v20, s11, v20
	v_add_u32_e32 v26, s11, v26
	v_add_u32_e32 v28, s11, v28
	v_add_u32_e32 v36, s11, v36
	v_lshlrev_b32_e32 v43, s7, v43
	v_mad_i64_i32 v[18:19], s[12:13], v18, s25, v[34:35]
	v_mad_i64_i32 v[22:23], s[12:13], v20, s25, v[34:35]
	v_mad_i64_i32 v[26:27], s[12:13], v26, s25, v[34:35]
	v_mad_i64_i32 v[30:31], s[12:13], v28, s25, v[34:35]
	v_mad_i64_i32 v[36:37], s[12:13], v36, s25, v[34:35]
	v_add_u32_e32 v43, s11, v43
	global_load_dwordx4 v[18:21], v[18:19], off
	s_nop 0
	global_load_dwordx4 v[22:25], v[22:23], off
	s_nop 0
	global_load_dwordx4 v[26:29], v[26:27], off
	s_nop 0
	global_load_dwordx4 v[30:33], v[30:31], off
	v_mad_i64_i32 v[44:45], s[12:13], v43, s25, v[34:35]
	global_load_dwordx4 v[50:53], v[36:37], off
	global_load_dwordx4 v[58:61], v[44:45], off
	v_or_b32_e32 v36, 6, v42
	v_or_b32_e32 v42, 7, v42
	v_lshlrev_b32_e32 v36, s7, v36
	v_lshlrev_b32_e32 v42, s7, v42
	v_add_u32_e32 v36, s11, v36
	v_add_u32_e32 v42, s11, v42
	v_mad_i64_i32 v[36:37], s[12:13], v36, s25, v[34:35]
	v_mad_i64_i32 v[34:35], s[12:13], v42, s25, v[34:35]
	global_load_dwordx4 v[70:73], v[36:37], off
	s_nop 0
	global_load_dwordx4 v[34:37], v[34:35], off
